# ln_rows: gamma/beta loads hoisted out of the row loop into registers, per-row flat loads and their full waits removed, row-B wait counted
# speedup vs baseline: 1.0121x; 1.0044x over previous
; DEV unsigned pk2(float lo, float hi) { f32x2_ v; v.x = lo; v.y = hi; return __builtin_bit_cast(unsigned, __builtin_convertvector(v, bf16x2_)); }
; DEV void ln_rows(float* hbuf, bf16* hb, const float* g, const float* bta, float* stats, bool write_h, int gw, int NGW, int lane) {
;     ...
;         for (int q = 0; q < 2; ++q) {
;             const int m = m0 + q * NGW;
;             const float mean = wave_sum(s[q], lane) * (1.f / DM); float s2 = 0.f;
; #pragma unroll
;             for (int j = 0; j < 4; ++j) { v[q][j] = v[q][j] - mean; s2 += (v[q][j].x * v[q][j].x + v[q][j].y * v[q][j].y) + (v[q][j].z * v[q][j].z + v[q][j].w * v[q][j].w); }
;             const float rstd = 1.f / sqrtf(wave_sum(s2, lane) * (1.f / DM) + 1e-5f);
;             if (lane == 0) { f32x2_ st2; st2.x = mean; st2.y = rstd; *(f32x2_*)(stats + 2 * m) = st2; }
;             f32x4* xr = (f32x4*)(hbuf + (size_t)m * DM) + lane;
;             unsigned long long* o8 = (unsigned long long*)(hb + (size_t)m * DM) + lane;
; #pragma unroll
;             for (int j = 0; j < 4; ++j) { const f32x4 gg = ((const f32x4*)g)[lane + 64 * j], bb = ((const f32x4*)bta)[lane + 64 * j];
;                 const f32x4 o = v[q][j] * rstd * gg + bb; if (write_h) xr[64 * j] = o;
;                 o8[64 * j] = (unsigned long long)pk2(o.x, o.y) | ((unsigned long long)pk2(o.z, o.w) << 32); }
.LBB0_318:
	s_or_b64 exec, exec, s[0:1]
	s_add_u32 s22, s50, 0x600000
	s_addc_u32 s23, s51, 0
	s_add_i32 s0, 0, 0x278e8
	s_waitcnt lgkmcnt(0)
	v_mov_b32_e32 v0, s0
	s_barrier
	ds_read2_b64 v[0:3], v0 offset1:1
	s_ashr_i32 s11, s57, 6
	v_readlane_b32 s0, v254, 6
	s_add_i32 s10, s11, s0
	v_and_b32_e32 v160, 63, v146
	s_cmp_lt_i32 s10, 0x8000
	s_waitcnt lgkmcnt(0)
	v_readfirstlane_b32 s6, v0
	v_readfirstlane_b32 s7, v1
	v_readfirstlane_b32 s8, v2
	v_readfirstlane_b32 s9, v3
	v_mov_b32_e32 v0, v160
	s_cselect_b64 s[12:13], -1, 0
	s_cmpk_gt_i32 s10, 0x7fff
	v_readlane_b32 s44, v254, 7
	v_readlane_b32 s45, v254, 8
	s_cbranch_scc1 .LBB0_325
	v_ashrrev_i32_e32 v1, 31, v0
	v_lshlrev_b64 v[2:3], 4, v[0:1]
	v_lshlrev_b32_e32 v4, 2, v0
	s_lshl_b32 s4, s2, 4
	s_lshl_b32 s5, s11, 1
	v_lshl_add_u64 v[32:33], s[48:49], 0, v[2:3]
	v_xor_b32_e32 v42, 64, v4
	v_xor_b32_e32 v43, 0x80, v4
	v_cmp_eq_u32_e64 s[0:1], 0, v0
	v_lshl_add_u64 v[34:35], v[0:1], 3, s[18:19]
	v_lshl_add_u64 v[36:37], s[6:7], 0, v[2:3]
	v_lshl_add_u64 v[38:39], s[8:9], 0, v[2:3]
	flat_load_dwordx4 v[64:67], v[36:37]
	flat_load_dwordx4 v[68:71], v[36:37] offset:1024
	flat_load_dwordx4 v[72:75], v[36:37] offset:2048
	flat_load_dwordx4 v[76:79], v[36:37] offset:3072
	flat_load_dwordx4 v[80:83], v[38:39]
	flat_load_dwordx4 v[84:87], v[38:39] offset:1024
	flat_load_dwordx4 v[88:91], v[38:39] offset:2048
	flat_load_dwordx4 v[92:95], v[38:39] offset:3072
	s_waitcnt vmcnt(0) lgkmcnt(0)
	s_add_i32 s8, s4, s5
	s_lshl_b32 s4, s58, 5
	s_lshl_b32 s5, s58, 4
	v_mov_b32_e32 v44, 0x3727c5ac
	s_mov_b32 s14, 0xf800000
	v_mov_b32_e32 v45, 0x260
	v_mov_b32_e32 v46, 0
	s_mov_b32 s26, s10
	s_branch .LBB0_321
.LBB0_320:
	s_or_b64 exec, exec, s[6:7]
	v_pk_mul_f32 v[14:15], v[18:19], v[12:13] op_sel_hi:[1,0]
	v_pk_mul_f32 v[16:17], v[16:17], v[12:13] op_sel_hi:[1,0]
	s_lshl_b64 s[6:7], s[24:25], 11
	v_lshl_add_u64 v[28:29], v[34:35], 0, s[6:7]
	v_pk_mul_f32 v[10:11], v[10:11], v[12:13] op_sel_hi:[1,0]
	v_pk_mul_f32 v[8:9], v[8:9], v[12:13] op_sel_hi:[1,0]
	v_pk_mul_f32 v[6:7], v[6:7], v[12:13] op_sel_hi:[1,0]
	v_pk_mul_f32 v[4:5], v[4:5], v[12:13] op_sel_hi:[1,0]
	v_pk_mul_f32 v[2:3], v[2:3], v[12:13] op_sel_hi:[1,0]
	v_pk_mul_f32 v[0:1], v[0:1], v[12:13] op_sel_hi:[1,0]
	s_add_i32 s26, s24, s44
	s_add_i32 s8, s8, s4
	s_cmp_lt_i32 s26, 0x8000
	v_pk_fma_f32 v[14:15], v[14:15], v[66:67], v[82:83]
	v_pk_fma_f32 v[16:17], v[16:17], v[64:65], v[80:81]
	s_nop 0
	v_cvt_pk_bf16_f32 v16, v16, v17
	v_cvt_pk_bf16_f32 v17, v14, v15
	global_store_dwordx2 v[28:29], v[16:17], off
	v_pk_fma_f32 v[10:11], v[10:11], v[70:71], v[86:87]
	v_pk_fma_f32 v[8:9], v[8:9], v[68:69], v[84:85]
	s_nop 0
	v_cvt_pk_bf16_f32 v8, v8, v9
	v_cvt_pk_bf16_f32 v9, v10, v11
	global_store_dwordx2 v[28:29], v[8:9], off offset:512
	v_pk_fma_f32 v[6:7], v[6:7], v[74:75], v[90:91]
	v_pk_fma_f32 v[4:5], v[4:5], v[72:73], v[88:89]
	s_nop 0
	v_cvt_pk_bf16_f32 v4, v4, v5
	v_cvt_pk_bf16_f32 v5, v6, v7
	global_store_dwordx2 v[28:29], v[4:5], off offset:1024
	v_pk_fma_f32 v[2:3], v[2:3], v[78:79], v[94:95]
	v_pk_fma_f32 v[0:1], v[0:1], v[76:77], v[92:93]
	s_nop 0
	v_cvt_pk_bf16_f32 v0, v0, v1
	v_cvt_pk_bf16_f32 v1, v2, v3
	global_store_dwordx2 v[28:29], v[0:1], off offset:1536
	s_cbranch_scc0 .LBB0_325

; DEV unsigned pk2(float lo, float hi) { f32x2_ v; v.x = lo; v.y = hi; return __builtin_bit_cast(unsigned, __builtin_convertvector(v, bf16x2_)); }
; DEV void ln_rows(float* hbuf, bf16* hb, const float* g, const float* bta, float* stats, bool write_h, int gw, int NGW, int lane) {
;     ...
;         for (int q = 0; q < 2; ++q) {
;             const int m = m0 + q * NGW;
;             const float mean = wave_sum(s[q], lane) * (1.f / DM); float s2 = 0.f;
; #pragma unroll
;             for (int j = 0; j < 4; ++j) { v[q][j] = v[q][j] - mean; s2 += (v[q][j].x * v[q][j].x + v[q][j].y * v[q][j].y) + (v[q][j].z * v[q][j].z + v[q][j].w * v[q][j].w); }
;             const float rstd = 1.f / sqrtf(wave_sum(s2, lane) * (1.f / DM) + 1e-5f);
;             if (lane == 0) { f32x2_ st2; st2.x = mean; st2.y = rstd; *(f32x2_*)(stats + 2 * m) = st2; }
;             f32x4* xr = (f32x4*)(hbuf + (size_t)m * DM) + lane;
;             unsigned long long* o8 = (unsigned long long*)(hb + (size_t)m * DM) + lane;
; #pragma unroll
;             for (int j = 0; j < 4; ++j) { const f32x4 gg = ((const f32x4*)g)[lane + 64 * j], bb = ((const f32x4*)bta)[lane + 64 * j];
;                 const f32x4 o = v[q][j] * rstd * gg + bb; if (write_h) xr[64 * j] = o;
;                 o8[64 * j] = (unsigned long long)pk2(o.x, o.y) | ((unsigned long long)pk2(o.z, o.w) << 32); }
.LBB0_323:
	s_or_b64 exec, exec, s[6:7]
	v_pk_mul_f32 v[40:41], v[40:41], v[22:23] op_sel_hi:[1,0]
	v_pk_mul_f32 v[28:29], v[28:29], v[22:23] op_sel_hi:[1,0]
	s_lshl_b64 s[6:7], s[26:27], 11
	v_lshl_add_u64 v[56:57], v[34:35], 0, s[6:7]
	v_pk_mul_f32 v[24:25], v[24:25], v[22:23] op_sel_hi:[1,0]
	s_waitcnt vmcnt(1)
	v_add_f32_e32 v47, v6, v7
	s_waitcnt lgkmcnt(0)
	v_pk_fma_f32 v[40:41], v[40:41], v[66:67], v[82:83]
	v_pk_fma_f32 v[28:29], v[28:29], v[64:65], v[80:81]
	s_nop 0
	v_cvt_pk_bf16_f32 v28, v28, v29
	v_cvt_pk_bf16_f32 v29, v40, v41
	global_store_dwordx2 v[56:57], v[28:29], off
	v_pk_mul_f32 v[28:29], v[30:31], v[22:23] op_sel_hi:[1,0]
	v_add_f32_e32 v23, v16, v17
	v_add_f32_e32 v40, v10, v11
	v_add_f32_e32 v41, v4, v5
	v_pk_fma_f32 v[28:29], v[28:29], v[70:71], v[86:87]
	v_pk_fma_f32 v[24:25], v[24:25], v[68:69], v[84:85]
	v_add_f32_e32 v52, v0, v1
	v_cvt_pk_bf16_f32 v24, v24, v25
	v_cvt_pk_bf16_f32 v25, v28, v29
	global_store_dwordx2 v[56:57], v[24:25], off offset:512
	v_add_f32_e32 v24, v18, v19
	v_add_f32_e32 v25, v8, v9
	v_add_f32_e32 v23, v23, v24
	v_add_f32_e32 v24, v25, v40
	v_add_f32_e32 v23, 0, v23
	v_add_f32_e32 v53, v2, v3
	v_add_f32_e32 v25, v41, v47
	v_add_f32_e32 v23, v23, v24
	v_add_f32_e32 v40, v52, v53
	v_add_f32_e32 v23, v23, v25
	v_add_f32_e32 v23, v23, v40
	s_nop 1
	v_add_f32_dpp v23, v23, v23 quad_perm:[1,0,3,2] row_mask:0xf bank_mask:0xf bound_ctrl:1
	s_nop 1
	v_add_f32_dpp v23, v23, v23 quad_perm:[2,3,0,1] row_mask:0xf bank_mask:0xf bound_ctrl:1
	s_nop 1
	v_add_f32_dpp v23, v23, v23 row_half_mirror row_mask:0xf bank_mask:0xf bound_ctrl:1
	s_nop 1
	v_add_f32_dpp v23, v23, v23 row_mirror row_mask:0xf bank_mask:0xf bound_ctrl:1
	ds_bpermute_b32 v24, v42, v23
	s_waitcnt lgkmcnt(0)
	v_add_f32_e32 v23, v23, v24
	v_pk_mul_f32 v[24:25], v[26:27], v[22:23] op_sel_hi:[1,0]
	v_pk_mul_f32 v[26:27], v[20:21], v[22:23] op_sel_hi:[1,0]
	ds_bpermute_b32 v40, v43, v23
	s_waitcnt lgkmcnt(0)
	v_add_f32_e32 v20, v23, v40
	v_fmamk_f32 v19, v20, 0xba800000, v19
	v_fmamk_f32 v17, v20, 0xba800000, v17
	v_fmamk_f32 v11, v20, 0xba800000, v11
	v_fmamk_f32 v9, v20, 0xba800000, v9
	v_fmamk_f32 v18, v20, 0xba800000, v18
	v_fmac_f32_e32 v16, 0xba800000, v20
	v_fmamk_f32 v10, v20, 0xba800000, v10
	v_fmac_f32_e32 v8, 0xba800000, v20
	v_fmamk_f32 v7, v20, 0xba800000, v7
	v_fmamk_f32 v5, v20, 0xba800000, v5
	v_mul_f32_e32 v21, v17, v17
	v_mul_f32_e32 v23, v19, v19
	v_mul_f32_e32 v40, v9, v9
	v_mul_f32_e32 v41, v11, v11
	v_fmamk_f32 v6, v20, 0xba800000, v6
	v_fmac_f32_e32 v4, 0xba800000, v20
	v_fmamk_f32 v3, v20, 0xba800000, v3
	v_fmamk_f32 v1, v20, 0xba800000, v1
	v_mul_f32_e32 v47, v5, v5
	v_fmac_f32_e32 v21, v16, v16
	v_fmac_f32_e32 v23, v18, v18
	v_fmac_f32_e32 v40, v8, v8
	v_fmac_f32_e32 v41, v10, v10
	v_fmamk_f32 v2, v20, 0xba800000, v2
	v_fmac_f32_e32 v0, 0xba800000, v20
	v_fmac_f32_e32 v47, v4, v4
	v_add_f32_e32 v21, v21, v23
	v_add_f32_e32 v23, v40, v41
	v_add_f32_e32 v21, v21, v23
	v_pk_fma_f32 v[24:25], v[24:25], v[74:75], v[90:91]
	v_pk_fma_f32 v[26:27], v[26:27], v[72:73], v[88:89]
	v_mul_f32_e32 v48, v7, v7
	v_cvt_pk_bf16_f32 v26, v26, v27
	v_cvt_pk_bf16_f32 v27, v24, v25
	global_store_dwordx2 v[56:57], v[26:27], off offset:1024
	v_mul_f32_e32 v49, v1, v1
	v_mul_f32_e32 v50, v3, v3
	v_fmac_f32_e32 v48, v6, v6
	v_fmac_f32_e32 v49, v0, v0
	v_fmac_f32_e32 v50, v2, v2
	v_add_f32_e32 v40, v47, v48
	v_add_f32_e32 v41, v49, v50
	v_add_f32_e32 v21, v40, v21
	v_add_f32_e32 v21, v41, v21
	s_nop 1
	v_add_f32_dpp v21, v21, v21 quad_perm:[1,0,3,2] row_mask:0xf bank_mask:0xf bound_ctrl:1
	s_nop 1
	v_add_f32_dpp v21, v21, v21 quad_perm:[2,3,0,1] row_mask:0xf bank_mask:0xf bound_ctrl:1
	s_nop 1
	v_add_f32_dpp v21, v21, v21 row_half_mirror row_mask:0xf bank_mask:0xf bound_ctrl:1
	s_nop 1
	v_add_f32_dpp v21, v21, v21 row_mirror row_mask:0xf bank_mask:0xf bound_ctrl:1
	ds_bpermute_b32 v23, v42, v21
	s_waitcnt lgkmcnt(0)
	v_add_f32_e32 v21, v21, v23
	ds_bpermute_b32 v23, v43, v21
	s_waitcnt lgkmcnt(0)
	v_add_f32_e32 v21, v21, v23
	v_fmamk_f32 v21, v21, 0x3a800000, v44
	v_mul_f32_e32 v23, 0x4f800000, v21
	v_cmp_gt_f32_e32 vcc, s14, v21
	s_nop 1
	v_cndmask_b32_e32 v21, v21, v23, vcc
	v_sqrt_f32_e32 v23, v21
	s_nop 0
	v_add_u32_e32 v40, -1, v23
	v_add_u32_e32 v41, 1, v23
	v_fma_f32 v47, -v40, v23, v21
	v_fma_f32 v48, -v41, v23, v21
	v_cmp_ge_f32_e64 s[6:7], 0, v47
	v_pk_mul_f32 v[14:15], v[14:15], v[22:23] op_sel_hi:[1,0]
	s_nop 0
	v_cndmask_b32_e64 v23, v23, v40, s[6:7]
	v_cmp_lt_f32_e64 s[6:7], 0, v48
	v_pk_fma_f32 v[14:15], v[14:15], v[78:79], v[94:95]
	v_cndmask_b32_e64 v23, v23, v41, s[6:7]
	v_mul_f32_e32 v40, 0x37800000, v23
	v_cndmask_b32_e32 v23, v23, v40, vcc
	v_cmp_class_f32_e32 vcc, v21, v45
	s_nop 1
	v_cndmask_b32_e32 v21, v23, v21, vcc
	v_div_scale_f32 v23, s[6:7], v21, v21, 1.0
	v_rcp_f32_e32 v40, v23
	v_pk_mul_f32 v[12:13], v[12:13], v[22:23] op_sel_hi:[1,0]
	v_div_scale_f32 v22, vcc, 1.0, v21, 1.0
	v_fma_f32 v41, -v23, v40, 1.0
	v_fmac_f32_e32 v40, v41, v40
	v_mul_f32_e32 v41, v22, v40
	v_fma_f32 v47, -v23, v41, v22
	v_fmac_f32_e32 v41, v47, v40
	v_fma_f32 v22, -v23, v41, v22
	v_pk_fma_f32 v[12:13], v[12:13], v[76:77], v[92:93]
	v_div_fmas_f32 v22, v22, v40, v41
	v_cvt_pk_bf16_f32 v12, v12, v13
	v_cvt_pk_bf16_f32 v13, v14, v15
	global_store_dwordx2 v[56:57], v[12:13], off offset:1536
	v_div_fixup_f32 v12, v22, v21, 1.0
	s_and_saveexec_b64 s[6:7], s[0:1]
	s_cbranch_execz .LBB0_320
	s_add_i32 s26, s5, s8
	s_ashr_i32 s27, s26, 31
	s_lshl_b64 s[26:27], s[26:27], 2
	s_add_u32 s26, s22, s26
	v_mul_f32_e32 v14, 0x3a800000, v20
	s_addc_u32 s27, s23, s27
	v_mov_b32_e32 v15, v12
	global_store_dwordx2 v46, v[14:15], s[26:27]
	s_branch .LBB0_320

; DEV unsigned pk2(float lo, float hi) { f32x2_ v; v.x = lo; v.y = hi; return __builtin_bit_cast(unsigned, __builtin_convertvector(v, bf16x2_)); }
; DEV void ln_rows(float* hbuf, bf16* hb, const float* g, const float* bta, float* stats, bool write_h, int gw, int NGW, int lane) {
;     ...
;             if (lane == 0) { f32x2_ st2; st2.x = mean; st2.y = rstd; *(f32x2_*)(stats + 2 * m) = st2; }
;             f32x4* xr = (f32x4*)(hbuf + (size_t)m * DM) + lane;
;             unsigned long long* o8 = (unsigned long long*)(hb + (size_t)m * DM) + lane;
; #pragma unroll
;             for (int j = 0; j < 4; ++j) { const f32x4 gg = ((const f32x4*)g)[lane + 64 * j], bb = ((const f32x4*)bta)[lane + 64 * j];
;                 const f32x4 o = v[q][j] * rstd * gg + bb; if (write_h) xr[64 * j] = o;
;                 o8[64 * j] = (unsigned long long)pk2(o.x, o.y) | ((unsigned long long)pk2(o.z, o.w) << 32); }
.LBB0_546:
	s_or_b64 exec, exec, s[0:1]
	s_add_i32 s0, 0, 0x27908
	s_waitcnt lgkmcnt(0)
	v_mov_b32_e32 v0, s0
	s_barrier
	ds_read2_b64 v[0:3], v0 offset1:1
	s_andn2_b64 vcc, exec, s[12:13]
	s_waitcnt lgkmcnt(0)
	v_readfirstlane_b32 s6, v0
	v_readfirstlane_b32 s7, v1
	v_readfirstlane_b32 s8, v2
	v_readfirstlane_b32 s9, v3
	s_cbranch_vccnz .LBB0_553
	v_ashrrev_i32_e32 v161, 31, v160
	s_add_u32 s4, s50, 0x640000
	v_lshlrev_b64 v[0:1], 4, v[160:161]
	s_addc_u32 s5, s51, 0
	v_lshlrev_b32_e32 v2, 2, v160
	v_lshl_add_u64 v[36:37], s[6:7], 0, v[0:1]
	s_lshl_b32 s6, s2, 4
	s_lshl_b32 s7, s11, 1
	v_lshl_add_u64 v[32:33], s[48:49], 0, v[0:1]
	v_xor_b32_e32 v42, 64, v2
	v_xor_b32_e32 v43, 0x80, v2
	v_cmp_eq_u32_e64 s[0:1], 0, v160
	v_lshl_add_u64 v[34:35], v[160:161], 3, s[18:19]
	v_lshl_add_u64 v[38:39], s[8:9], 0, v[0:1]
	flat_load_dwordx4 v[64:67], v[36:37]
	flat_load_dwordx4 v[68:71], v[36:37] offset:1024
	flat_load_dwordx4 v[72:75], v[36:37] offset:2048
	flat_load_dwordx4 v[76:79], v[36:37] offset:3072
	flat_load_dwordx4 v[80:83], v[38:39]
	flat_load_dwordx4 v[84:87], v[38:39] offset:1024
	flat_load_dwordx4 v[88:91], v[38:39] offset:2048
	flat_load_dwordx4 v[92:95], v[38:39] offset:3072
	s_waitcnt vmcnt(0) lgkmcnt(0)
	s_add_i32 s8, s6, s7
	s_lshl_b32 s14, s58, 5
	s_lshl_b32 s15, s58, 4
	v_mov_b32_e32 v44, 0x3727c5ac
	s_mov_b32 s18, 0xf800000
	v_mov_b32_e32 v45, 0x260
	v_mov_b32_e32 v46, 0
	s_branch .LBB0_549
.LBB0_548:
	s_or_b64 exec, exec, s[6:7]
	v_pk_mul_f32 v[14:15], v[18:19], v[12:13] op_sel_hi:[1,0]
	v_pk_mul_f32 v[16:17], v[16:17], v[12:13] op_sel_hi:[1,0]
	s_lshl_b64 s[6:7], s[12:13], 11
	v_lshl_add_u64 v[28:29], v[34:35], 0, s[6:7]
	v_pk_mul_f32 v[10:11], v[10:11], v[12:13] op_sel_hi:[1,0]
	v_pk_mul_f32 v[8:9], v[8:9], v[12:13] op_sel_hi:[1,0]
	v_pk_mul_f32 v[6:7], v[6:7], v[12:13] op_sel_hi:[1,0]
	v_pk_mul_f32 v[4:5], v[4:5], v[12:13] op_sel_hi:[1,0]
	v_pk_mul_f32 v[2:3], v[2:3], v[12:13] op_sel_hi:[1,0]
	v_pk_mul_f32 v[0:1], v[0:1], v[12:13] op_sel_hi:[1,0]
	s_add_i32 s10, s12, s44
	s_add_i32 s8, s8, s14
	s_cmp_lt_i32 s10, 0x8000
	v_pk_fma_f32 v[14:15], v[14:15], v[66:67], v[82:83]
	v_pk_fma_f32 v[16:17], v[16:17], v[64:65], v[80:81]
	s_nop 0
	v_cvt_pk_bf16_f32 v16, v16, v17
	v_cvt_pk_bf16_f32 v17, v14, v15
	global_store_dwordx2 v[28:29], v[16:17], off
	v_pk_fma_f32 v[10:11], v[10:11], v[70:71], v[86:87]
	v_pk_fma_f32 v[8:9], v[8:9], v[68:69], v[84:85]
	s_nop 0
	v_cvt_pk_bf16_f32 v8, v8, v9
	v_cvt_pk_bf16_f32 v9, v10, v11
	global_store_dwordx2 v[28:29], v[8:9], off offset:512
	v_pk_fma_f32 v[6:7], v[6:7], v[74:75], v[90:91]
	v_pk_fma_f32 v[4:5], v[4:5], v[72:73], v[88:89]
	s_nop 0
	v_cvt_pk_bf16_f32 v4, v4, v5
	v_cvt_pk_bf16_f32 v5, v6, v7
	global_store_dwordx2 v[28:29], v[4:5], off offset:1024
	v_pk_fma_f32 v[2:3], v[2:3], v[78:79], v[94:95]
	v_pk_fma_f32 v[0:1], v[0:1], v[76:77], v[92:93]
	s_nop 0
	v_cvt_pk_bf16_f32 v0, v0, v1
	v_cvt_pk_bf16_f32 v1, v2, v3
	global_store_dwordx2 v[28:29], v[0:1], off offset:1536
	s_cbranch_scc0 .LBB0_553

; DEV unsigned pk2(float lo, float hi) { f32x2_ v; v.x = lo; v.y = hi; return __builtin_bit_cast(unsigned, __builtin_convertvector(v, bf16x2_)); }
; DEV void ln_rows(float* hbuf, bf16* hb, const float* g, const float* bta, float* stats, bool write_h, int gw, int NGW, int lane) {
;     ...
;         for (int q = 0; q < 2; ++q) {
;             const int m = m0 + q * NGW;
;             const float mean = wave_sum(s[q], lane) * (1.f / DM); float s2 = 0.f;
; #pragma unroll
;             for (int j = 0; j < 4; ++j) { v[q][j] = v[q][j] - mean; s2 += (v[q][j].x * v[q][j].x + v[q][j].y * v[q][j].y) + (v[q][j].z * v[q][j].z + v[q][j].w * v[q][j].w); }
;             const float rstd = 1.f / sqrtf(wave_sum(s2, lane) * (1.f / DM) + 1e-5f);
;             if (lane == 0) { f32x2_ st2; st2.x = mean; st2.y = rstd; *(f32x2_*)(stats + 2 * m) = st2; }
;             f32x4* xr = (f32x4*)(hbuf + (size_t)m * DM) + lane;
;             unsigned long long* o8 = (unsigned long long*)(hb + (size_t)m * DM) + lane;
; #pragma unroll
;             for (int j = 0; j < 4; ++j) { const f32x4 gg = ((const f32x4*)g)[lane + 64 * j], bb = ((const f32x4*)bta)[lane + 64 * j];
;                 const f32x4 o = v[q][j] * rstd * gg + bb; if (write_h) xr[64 * j] = o;
;                 o8[64 * j] = (unsigned long long)pk2(o.x, o.y) | ((unsigned long long)pk2(o.z, o.w) << 32); }
.LBB0_551:
	s_or_b64 exec, exec, s[6:7]
	v_pk_mul_f32 v[40:41], v[40:41], v[22:23] op_sel_hi:[1,0]
	v_pk_mul_f32 v[28:29], v[28:29], v[22:23] op_sel_hi:[1,0]
	s_lshl_b64 s[6:7], s[10:11], 11
	v_lshl_add_u64 v[56:57], v[34:35], 0, s[6:7]
	v_pk_mul_f32 v[24:25], v[24:25], v[22:23] op_sel_hi:[1,0]
	s_waitcnt vmcnt(1)
	v_add_f32_e32 v47, v6, v7
	s_waitcnt lgkmcnt(0)
	v_pk_fma_f32 v[40:41], v[40:41], v[66:67], v[82:83]
	v_pk_fma_f32 v[28:29], v[28:29], v[64:65], v[80:81]
	s_nop 0
	v_cvt_pk_bf16_f32 v28, v28, v29
	v_cvt_pk_bf16_f32 v29, v40, v41
	global_store_dwordx2 v[56:57], v[28:29], off
	v_pk_mul_f32 v[28:29], v[30:31], v[22:23] op_sel_hi:[1,0]
	v_add_f32_e32 v23, v16, v17
	v_add_f32_e32 v40, v10, v11
	v_add_f32_e32 v41, v4, v5
	v_pk_fma_f32 v[28:29], v[28:29], v[70:71], v[86:87]
	v_pk_fma_f32 v[24:25], v[24:25], v[68:69], v[84:85]
	v_add_f32_e32 v52, v0, v1
	v_cvt_pk_bf16_f32 v24, v24, v25
	v_cvt_pk_bf16_f32 v25, v28, v29
	global_store_dwordx2 v[56:57], v[24:25], off offset:512
	v_add_f32_e32 v24, v18, v19
	v_add_f32_e32 v25, v8, v9
	v_add_f32_e32 v23, v23, v24
	v_add_f32_e32 v24, v25, v40
	v_add_f32_e32 v23, 0, v23
	v_add_f32_e32 v53, v2, v3
	v_add_f32_e32 v25, v41, v47
	v_add_f32_e32 v23, v23, v24
	v_add_f32_e32 v40, v52, v53
	v_add_f32_e32 v23, v23, v25
	v_add_f32_e32 v23, v23, v40
	s_nop 1
	v_add_f32_dpp v23, v23, v23 quad_perm:[1,0,3,2] row_mask:0xf bank_mask:0xf bound_ctrl:1
	s_nop 1
	v_add_f32_dpp v23, v23, v23 quad_perm:[2,3,0,1] row_mask:0xf bank_mask:0xf bound_ctrl:1
	s_nop 1
	v_add_f32_dpp v23, v23, v23 row_half_mirror row_mask:0xf bank_mask:0xf bound_ctrl:1
	s_nop 1
	v_add_f32_dpp v23, v23, v23 row_mirror row_mask:0xf bank_mask:0xf bound_ctrl:1
	ds_bpermute_b32 v24, v42, v23
	s_waitcnt lgkmcnt(0)
	v_add_f32_e32 v23, v23, v24
	v_pk_mul_f32 v[24:25], v[26:27], v[22:23] op_sel_hi:[1,0]
	v_pk_mul_f32 v[26:27], v[20:21], v[22:23] op_sel_hi:[1,0]
	ds_bpermute_b32 v40, v43, v23
	s_waitcnt lgkmcnt(0)
	v_add_f32_e32 v20, v23, v40
	v_fmamk_f32 v19, v20, 0xba800000, v19
	v_fmamk_f32 v17, v20, 0xba800000, v17
	v_fmamk_f32 v11, v20, 0xba800000, v11
	v_fmamk_f32 v9, v20, 0xba800000, v9
	v_fmamk_f32 v18, v20, 0xba800000, v18
	v_fmac_f32_e32 v16, 0xba800000, v20
	v_fmamk_f32 v10, v20, 0xba800000, v10
	v_fmac_f32_e32 v8, 0xba800000, v20
	v_fmamk_f32 v7, v20, 0xba800000, v7
	v_fmamk_f32 v5, v20, 0xba800000, v5
	v_mul_f32_e32 v21, v17, v17
	v_mul_f32_e32 v23, v19, v19
	v_mul_f32_e32 v40, v9, v9
	v_mul_f32_e32 v41, v11, v11
	v_fmamk_f32 v6, v20, 0xba800000, v6
	v_fmac_f32_e32 v4, 0xba800000, v20
	v_fmamk_f32 v3, v20, 0xba800000, v3
	v_fmamk_f32 v1, v20, 0xba800000, v1
	v_mul_f32_e32 v47, v5, v5
	v_fmac_f32_e32 v21, v16, v16
	v_fmac_f32_e32 v23, v18, v18
	v_fmac_f32_e32 v40, v8, v8
	v_fmac_f32_e32 v41, v10, v10
	v_fmamk_f32 v2, v20, 0xba800000, v2
	v_fmac_f32_e32 v0, 0xba800000, v20
	v_fmac_f32_e32 v47, v4, v4
	v_add_f32_e32 v21, v21, v23
	v_add_f32_e32 v23, v40, v41
	v_add_f32_e32 v21, v21, v23
	v_pk_fma_f32 v[24:25], v[24:25], v[74:75], v[90:91]
	v_pk_fma_f32 v[26:27], v[26:27], v[72:73], v[88:89]
	v_mul_f32_e32 v48, v7, v7
	v_cvt_pk_bf16_f32 v26, v26, v27
	v_cvt_pk_bf16_f32 v27, v24, v25
	global_store_dwordx2 v[56:57], v[26:27], off offset:1024
	v_mul_f32_e32 v49, v1, v1
	v_mul_f32_e32 v50, v3, v3
	v_fmac_f32_e32 v48, v6, v6
	v_fmac_f32_e32 v49, v0, v0
	v_fmac_f32_e32 v50, v2, v2
	v_add_f32_e32 v40, v47, v48
	v_add_f32_e32 v41, v49, v50
	v_add_f32_e32 v21, v40, v21
	v_add_f32_e32 v21, v41, v21
	s_nop 1
	v_add_f32_dpp v21, v21, v21 quad_perm:[1,0,3,2] row_mask:0xf bank_mask:0xf bound_ctrl:1
	s_nop 1
	v_add_f32_dpp v21, v21, v21 quad_perm:[2,3,0,1] row_mask:0xf bank_mask:0xf bound_ctrl:1
	s_nop 1
	v_add_f32_dpp v21, v21, v21 row_half_mirror row_mask:0xf bank_mask:0xf bound_ctrl:1
	s_nop 1
	v_add_f32_dpp v21, v21, v21 row_mirror row_mask:0xf bank_mask:0xf bound_ctrl:1
	ds_bpermute_b32 v23, v42, v21
	s_waitcnt lgkmcnt(0)
	v_add_f32_e32 v21, v21, v23
	ds_bpermute_b32 v23, v43, v21
	s_waitcnt lgkmcnt(0)
	v_add_f32_e32 v21, v21, v23
	v_fmamk_f32 v21, v21, 0x3a800000, v44
	v_mul_f32_e32 v23, 0x4f800000, v21
	v_cmp_gt_f32_e32 vcc, s18, v21
	s_nop 1
	v_cndmask_b32_e32 v21, v21, v23, vcc
	v_sqrt_f32_e32 v23, v21
	s_nop 0
	v_add_u32_e32 v40, -1, v23
	v_add_u32_e32 v41, 1, v23
	v_fma_f32 v47, -v40, v23, v21
	v_fma_f32 v48, -v41, v23, v21
	v_cmp_ge_f32_e64 s[6:7], 0, v47
	v_pk_mul_f32 v[14:15], v[14:15], v[22:23] op_sel_hi:[1,0]
	s_nop 0
	v_cndmask_b32_e64 v23, v23, v40, s[6:7]
	v_cmp_lt_f32_e64 s[6:7], 0, v48
	v_pk_fma_f32 v[14:15], v[14:15], v[78:79], v[94:95]
	v_cndmask_b32_e64 v23, v23, v41, s[6:7]
	v_mul_f32_e32 v40, 0x37800000, v23
	v_cndmask_b32_e32 v23, v23, v40, vcc
	v_cmp_class_f32_e32 vcc, v21, v45
	s_nop 1
	v_cndmask_b32_e32 v21, v23, v21, vcc
	v_div_scale_f32 v23, s[6:7], v21, v21, 1.0
	v_rcp_f32_e32 v40, v23
	v_pk_mul_f32 v[12:13], v[12:13], v[22:23] op_sel_hi:[1,0]
	v_div_scale_f32 v22, vcc, 1.0, v21, 1.0
	v_fma_f32 v41, -v23, v40, 1.0
	v_fmac_f32_e32 v40, v41, v40
	v_mul_f32_e32 v41, v22, v40
	v_fma_f32 v47, -v23, v41, v22
	v_fmac_f32_e32 v41, v47, v40
	v_fma_f32 v22, -v23, v41, v22
	v_pk_fma_f32 v[12:13], v[12:13], v[76:77], v[92:93]
	v_div_fmas_f32 v22, v22, v40, v41
	v_cvt_pk_bf16_f32 v12, v12, v13
	v_cvt_pk_bf16_f32 v13, v14, v15
	global_store_dwordx2 v[56:57], v[12:13], off offset:1536
	v_div_fixup_f32 v12, v22, v21, 1.0
	s_and_saveexec_b64 s[6:7], s[0:1]
	s_cbranch_execz .LBB0_548
	s_add_i32 s10, s15, s8
	s_ashr_i32 s11, s10, 31
	s_lshl_b64 s[10:11], s[10:11], 2
	s_add_u32 s10, s4, s10
	v_mul_f32_e32 v14, 0x3a800000, v20
	s_addc_u32 s11, s5, s11
	v_mov_b32_e32 v15, v12
	global_store_dwordx2 v46, v[14:15], s[10:11]
	s_branch .LBB0_548

; DEV unsigned pk2(float lo, float hi) { f32x2_ v; v.x = lo; v.y = hi; return __builtin_bit_cast(unsigned, __builtin_convertvector(v, bf16x2_)); }
; DEV void ln_rows(float* hbuf, bf16* hb, const float* g, const float* bta, float* stats, bool write_h, int gw, int NGW, int lane) {
;     ...
;             if (lane == 0) { f32x2_ st2; st2.x = mean; st2.y = rstd; *(f32x2_*)(stats + 2 * m) = st2; }
;             f32x4* xr = (f32x4*)(hbuf + (size_t)m * DM) + lane;
;             unsigned long long* o8 = (unsigned long long*)(hb + (size_t)m * DM) + lane;
; #pragma unroll
;             for (int j = 0; j < 4; ++j) { const f32x4 gg = ((const f32x4*)g)[lane + 64 * j], bb = ((const f32x4*)bta)[lane + 64 * j];
;                 const f32x4 o = v[q][j] * rstd * gg + bb; if (write_h) xr[64 * j] = o;
;                 o8[64 * j] = (unsigned long long)pk2(o.x, o.y) | ((unsigned long long)pk2(o.z, o.w) << 32); }
.LBB0_1252:
	s_or_b64 exec, exec, s[0:1]
	s_add_u32 s18, s50, 0x600000
	s_addc_u32 s19, s51, 0
	s_add_i32 s0, 0, 0x27928
	s_waitcnt lgkmcnt(0)
	v_mov_b32_e32 v0, s0
	s_barrier
	ds_read2_b64 v[0:3], v0 offset1:1
	v_readlane_b32 s0, v254, 15
	s_ashr_i32 s13, s0, 6
	v_readlane_b32 s0, v254, 6
	s_add_i32 s12, s13, s0
	v_and_b32_e32 v160, 63, v160
	s_cmp_lt_i32 s12, 0x8000
	s_waitcnt lgkmcnt(0)
	v_readfirstlane_b32 s6, v0
	v_readfirstlane_b32 s7, v1
	v_readfirstlane_b32 s8, v2
	v_readfirstlane_b32 s9, v3
	v_mov_b32_e32 v0, v160
	s_cselect_b64 s[16:17], -1, 0
	s_cmpk_gt_i32 s12, 0x7fff
	s_cbranch_scc1 .LBB0_1259
	v_ashrrev_i32_e32 v1, 31, v0
	v_lshlrev_b64 v[2:3], 4, v[0:1]
	v_lshlrev_b32_e32 v4, 2, v0
	s_lshl_b32 s4, s2, 4
	s_lshl_b32 s5, s13, 1
	v_lshl_add_u64 v[32:33], s[48:49], 0, v[2:3]
	v_xor_b32_e32 v42, 64, v4
	v_xor_b32_e32 v43, 0x80, v4
	v_cmp_eq_u32_e64 s[0:1], 0, v0
	v_lshl_add_u64 v[34:35], v[0:1], 3, s[70:71]
	v_lshl_add_u64 v[36:37], s[6:7], 0, v[2:3]
	v_lshl_add_u64 v[38:39], s[8:9], 0, v[2:3]
	flat_load_dwordx4 v[64:67], v[36:37]
	flat_load_dwordx4 v[68:71], v[36:37] offset:1024
	flat_load_dwordx4 v[72:75], v[36:37] offset:2048
	flat_load_dwordx4 v[76:79], v[36:37] offset:3072
	flat_load_dwordx4 v[80:83], v[38:39]
	flat_load_dwordx4 v[84:87], v[38:39] offset:1024
	flat_load_dwordx4 v[88:91], v[38:39] offset:2048
	flat_load_dwordx4 v[92:95], v[38:39] offset:3072
	s_waitcnt vmcnt(0) lgkmcnt(0)
	s_add_i32 s8, s4, s5
	s_lshl_b32 s4, s58, 5
	s_lshl_b32 s5, s58, 4
	v_mov_b32_e32 v44, 0x3727c5ac
	s_mov_b32 s14, 0xf800000
	v_mov_b32_e32 v45, 0x260
	v_mov_b32_e32 v46, 0
	s_mov_b32 s22, s12
	s_branch .LBB0_1255
.LBB0_1254:
	s_or_b64 exec, exec, s[6:7]
	v_pk_mul_f32 v[14:15], v[18:19], v[12:13] op_sel_hi:[1,0]
	v_pk_mul_f32 v[16:17], v[16:17], v[12:13] op_sel_hi:[1,0]
	s_lshl_b64 s[6:7], s[20:21], 11
	v_lshl_add_u64 v[28:29], v[34:35], 0, s[6:7]
	v_pk_mul_f32 v[10:11], v[10:11], v[12:13] op_sel_hi:[1,0]
	v_pk_mul_f32 v[8:9], v[8:9], v[12:13] op_sel_hi:[1,0]
	v_pk_mul_f32 v[6:7], v[6:7], v[12:13] op_sel_hi:[1,0]
	v_pk_mul_f32 v[4:5], v[4:5], v[12:13] op_sel_hi:[1,0]
	v_pk_mul_f32 v[2:3], v[2:3], v[12:13] op_sel_hi:[1,0]
	v_pk_mul_f32 v[0:1], v[0:1], v[12:13] op_sel_hi:[1,0]
	s_add_i32 s22, s20, s62
	s_add_i32 s8, s8, s4
	s_cmp_lt_i32 s22, 0x8000
	v_pk_fma_f32 v[14:15], v[14:15], v[66:67], v[82:83]
	v_pk_fma_f32 v[16:17], v[16:17], v[64:65], v[80:81]
	s_nop 0
	v_cvt_pk_bf16_f32 v16, v16, v17
	v_cvt_pk_bf16_f32 v17, v14, v15
	global_store_dwordx2 v[28:29], v[16:17], off
	v_pk_fma_f32 v[10:11], v[10:11], v[70:71], v[86:87]
	v_pk_fma_f32 v[8:9], v[8:9], v[68:69], v[84:85]
	s_nop 0
	v_cvt_pk_bf16_f32 v8, v8, v9
	v_cvt_pk_bf16_f32 v9, v10, v11
	global_store_dwordx2 v[28:29], v[8:9], off offset:512
	v_pk_fma_f32 v[6:7], v[6:7], v[74:75], v[90:91]
	v_pk_fma_f32 v[4:5], v[4:5], v[72:73], v[88:89]
	s_nop 0
	v_cvt_pk_bf16_f32 v4, v4, v5
	v_cvt_pk_bf16_f32 v5, v6, v7
	global_store_dwordx2 v[28:29], v[4:5], off offset:1024
	v_pk_fma_f32 v[2:3], v[2:3], v[78:79], v[94:95]
	v_pk_fma_f32 v[0:1], v[0:1], v[76:77], v[92:93]
	s_nop 0
	v_cvt_pk_bf16_f32 v0, v0, v1
	v_cvt_pk_bf16_f32 v1, v2, v3
	global_store_dwordx2 v[28:29], v[0:1], off offset:1536
	s_cbranch_scc0 .LBB0_1259

; DEV unsigned pk2(float lo, float hi) { f32x2_ v; v.x = lo; v.y = hi; return __builtin_bit_cast(unsigned, __builtin_convertvector(v, bf16x2_)); }
; DEV void ln_rows(float* hbuf, bf16* hb, const float* g, const float* bta, float* stats, bool write_h, int gw, int NGW, int lane) {
;     ...
;         for (int q = 0; q < 2; ++q) {
;             const int m = m0 + q * NGW;
;             const float mean = wave_sum(s[q], lane) * (1.f / DM); float s2 = 0.f;
; #pragma unroll
;             for (int j = 0; j < 4; ++j) { v[q][j] = v[q][j] - mean; s2 += (v[q][j].x * v[q][j].x + v[q][j].y * v[q][j].y) + (v[q][j].z * v[q][j].z + v[q][j].w * v[q][j].w); }
;             const float rstd = 1.f / sqrtf(wave_sum(s2, lane) * (1.f / DM) + 1e-5f);
;             if (lane == 0) { f32x2_ st2; st2.x = mean; st2.y = rstd; *(f32x2_*)(stats + 2 * m) = st2; }
;             f32x4* xr = (f32x4*)(hbuf + (size_t)m * DM) + lane;
;             unsigned long long* o8 = (unsigned long long*)(hb + (size_t)m * DM) + lane;
; #pragma unroll
;             for (int j = 0; j < 4; ++j) { const f32x4 gg = ((const f32x4*)g)[lane + 64 * j], bb = ((const f32x4*)bta)[lane + 64 * j];
;                 const f32x4 o = v[q][j] * rstd * gg + bb; if (write_h) xr[64 * j] = o;
;                 o8[64 * j] = (unsigned long long)pk2(o.x, o.y) | ((unsigned long long)pk2(o.z, o.w) << 32); }
.LBB0_1257:
	s_or_b64 exec, exec, s[6:7]
	v_pk_mul_f32 v[40:41], v[40:41], v[22:23] op_sel_hi:[1,0]
	v_pk_mul_f32 v[28:29], v[28:29], v[22:23] op_sel_hi:[1,0]
	s_lshl_b64 s[6:7], s[22:23], 11
	v_lshl_add_u64 v[56:57], v[34:35], 0, s[6:7]
	v_pk_mul_f32 v[24:25], v[24:25], v[22:23] op_sel_hi:[1,0]
	s_waitcnt vmcnt(1)
	v_add_f32_e32 v47, v6, v7
	s_waitcnt lgkmcnt(0)
	v_pk_fma_f32 v[40:41], v[40:41], v[66:67], v[82:83]
	v_pk_fma_f32 v[28:29], v[28:29], v[64:65], v[80:81]
	s_nop 0
	v_cvt_pk_bf16_f32 v28, v28, v29
	v_cvt_pk_bf16_f32 v29, v40, v41
	global_store_dwordx2 v[56:57], v[28:29], off
	v_pk_mul_f32 v[28:29], v[30:31], v[22:23] op_sel_hi:[1,0]
	v_add_f32_e32 v23, v16, v17
	v_add_f32_e32 v40, v10, v11
	v_add_f32_e32 v41, v4, v5
	v_pk_fma_f32 v[28:29], v[28:29], v[70:71], v[86:87]
	v_pk_fma_f32 v[24:25], v[24:25], v[68:69], v[84:85]
	v_add_f32_e32 v52, v0, v1
	v_cvt_pk_bf16_f32 v24, v24, v25
	v_cvt_pk_bf16_f32 v25, v28, v29
	global_store_dwordx2 v[56:57], v[24:25], off offset:512
	v_add_f32_e32 v24, v18, v19
	v_add_f32_e32 v25, v8, v9
	v_add_f32_e32 v23, v23, v24
	v_add_f32_e32 v24, v25, v40
	v_add_f32_e32 v23, 0, v23
	v_add_f32_e32 v53, v2, v3
	v_add_f32_e32 v25, v41, v47
	v_add_f32_e32 v23, v23, v24
	v_add_f32_e32 v40, v52, v53
	v_add_f32_e32 v23, v23, v25
	v_add_f32_e32 v23, v23, v40
	s_nop 1
	v_add_f32_dpp v23, v23, v23 quad_perm:[1,0,3,2] row_mask:0xf bank_mask:0xf bound_ctrl:1
	s_nop 1
	v_add_f32_dpp v23, v23, v23 quad_perm:[2,3,0,1] row_mask:0xf bank_mask:0xf bound_ctrl:1
	s_nop 1
	v_add_f32_dpp v23, v23, v23 row_half_mirror row_mask:0xf bank_mask:0xf bound_ctrl:1
	s_nop 1
	v_add_f32_dpp v23, v23, v23 row_mirror row_mask:0xf bank_mask:0xf bound_ctrl:1
	ds_bpermute_b32 v24, v42, v23
	s_waitcnt lgkmcnt(0)
	v_add_f32_e32 v23, v23, v24
	v_pk_mul_f32 v[24:25], v[26:27], v[22:23] op_sel_hi:[1,0]
	v_pk_mul_f32 v[26:27], v[20:21], v[22:23] op_sel_hi:[1,0]
	ds_bpermute_b32 v40, v43, v23
	s_waitcnt lgkmcnt(0)
	v_add_f32_e32 v20, v23, v40
	v_fmamk_f32 v19, v20, 0xba800000, v19
	v_fmamk_f32 v17, v20, 0xba800000, v17
	v_fmamk_f32 v11, v20, 0xba800000, v11
	v_fmamk_f32 v9, v20, 0xba800000, v9
	v_fmamk_f32 v18, v20, 0xba800000, v18
	v_fmac_f32_e32 v16, 0xba800000, v20
	v_fmamk_f32 v10, v20, 0xba800000, v10
	v_fmac_f32_e32 v8, 0xba800000, v20
	v_fmamk_f32 v7, v20, 0xba800000, v7
	v_fmamk_f32 v5, v20, 0xba800000, v5
	v_mul_f32_e32 v21, v17, v17
	v_mul_f32_e32 v23, v19, v19
	v_mul_f32_e32 v40, v9, v9
	v_mul_f32_e32 v41, v11, v11
	v_fmamk_f32 v6, v20, 0xba800000, v6
	v_fmac_f32_e32 v4, 0xba800000, v20
	v_fmamk_f32 v3, v20, 0xba800000, v3
	v_fmamk_f32 v1, v20, 0xba800000, v1
	v_mul_f32_e32 v47, v5, v5
	v_fmac_f32_e32 v21, v16, v16
	v_fmac_f32_e32 v23, v18, v18
	v_fmac_f32_e32 v40, v8, v8
	v_fmac_f32_e32 v41, v10, v10
	v_fmamk_f32 v2, v20, 0xba800000, v2
	v_fmac_f32_e32 v0, 0xba800000, v20
	v_fmac_f32_e32 v47, v4, v4
	v_add_f32_e32 v21, v21, v23
	v_add_f32_e32 v23, v40, v41
	v_add_f32_e32 v21, v21, v23
	v_pk_fma_f32 v[24:25], v[24:25], v[74:75], v[90:91]
	v_pk_fma_f32 v[26:27], v[26:27], v[72:73], v[88:89]
	v_mul_f32_e32 v48, v7, v7
	v_cvt_pk_bf16_f32 v26, v26, v27
	v_cvt_pk_bf16_f32 v27, v24, v25
	global_store_dwordx2 v[56:57], v[26:27], off offset:1024
	v_mul_f32_e32 v49, v1, v1
	v_mul_f32_e32 v50, v3, v3
	v_fmac_f32_e32 v48, v6, v6
	v_fmac_f32_e32 v49, v0, v0
	v_fmac_f32_e32 v50, v2, v2
	v_add_f32_e32 v40, v47, v48
	v_add_f32_e32 v41, v49, v50
	v_add_f32_e32 v21, v40, v21
	v_add_f32_e32 v21, v41, v21
	s_nop 1
	v_add_f32_dpp v21, v21, v21 quad_perm:[1,0,3,2] row_mask:0xf bank_mask:0xf bound_ctrl:1
	s_nop 1
	v_add_f32_dpp v21, v21, v21 quad_perm:[2,3,0,1] row_mask:0xf bank_mask:0xf bound_ctrl:1
	s_nop 1
	v_add_f32_dpp v21, v21, v21 row_half_mirror row_mask:0xf bank_mask:0xf bound_ctrl:1
	s_nop 1
	v_add_f32_dpp v21, v21, v21 row_mirror row_mask:0xf bank_mask:0xf bound_ctrl:1
	ds_bpermute_b32 v23, v42, v21
	s_waitcnt lgkmcnt(0)
	v_add_f32_e32 v21, v21, v23
	ds_bpermute_b32 v23, v43, v21
	s_waitcnt lgkmcnt(0)
	v_add_f32_e32 v21, v21, v23
	v_fmamk_f32 v21, v21, 0x3a800000, v44
	v_mul_f32_e32 v23, 0x4f800000, v21
	v_cmp_gt_f32_e32 vcc, s14, v21
	s_nop 1
	v_cndmask_b32_e32 v21, v21, v23, vcc
	v_sqrt_f32_e32 v23, v21
	s_nop 0
	v_add_u32_e32 v40, -1, v23
	v_add_u32_e32 v41, 1, v23
	v_fma_f32 v47, -v40, v23, v21
	v_fma_f32 v48, -v41, v23, v21
	v_cmp_ge_f32_e64 s[6:7], 0, v47
	v_pk_mul_f32 v[14:15], v[14:15], v[22:23] op_sel_hi:[1,0]
	s_nop 0
	v_cndmask_b32_e64 v23, v23, v40, s[6:7]
	v_cmp_lt_f32_e64 s[6:7], 0, v48
	v_pk_fma_f32 v[14:15], v[14:15], v[78:79], v[94:95]
	v_cndmask_b32_e64 v23, v23, v41, s[6:7]
	v_mul_f32_e32 v40, 0x37800000, v23
	v_cndmask_b32_e32 v23, v23, v40, vcc
	v_cmp_class_f32_e32 vcc, v21, v45
	s_nop 1
	v_cndmask_b32_e32 v21, v23, v21, vcc
	v_div_scale_f32 v23, s[6:7], v21, v21, 1.0
	v_rcp_f32_e32 v40, v23
	v_pk_mul_f32 v[12:13], v[12:13], v[22:23] op_sel_hi:[1,0]
	v_div_scale_f32 v22, vcc, 1.0, v21, 1.0
	v_fma_f32 v41, -v23, v40, 1.0
	v_fmac_f32_e32 v40, v41, v40
	v_mul_f32_e32 v41, v22, v40
	v_fma_f32 v47, -v23, v41, v22
	v_fmac_f32_e32 v41, v47, v40
	v_fma_f32 v22, -v23, v41, v22
	v_pk_fma_f32 v[12:13], v[12:13], v[76:77], v[92:93]
	v_div_fmas_f32 v22, v22, v40, v41
	v_cvt_pk_bf16_f32 v12, v12, v13
	v_cvt_pk_bf16_f32 v13, v14, v15
	global_store_dwordx2 v[56:57], v[12:13], off offset:1536
	v_div_fixup_f32 v12, v22, v21, 1.0
	s_and_saveexec_b64 s[6:7], s[0:1]
	s_cbranch_execz .LBB0_1254
	s_add_i32 s22, s5, s8
	s_ashr_i32 s23, s22, 31
	s_lshl_b64 s[22:23], s[22:23], 2
	s_add_u32 s22, s18, s22
	v_mul_f32_e32 v14, 0x3a800000, v20
	s_addc_u32 s23, s19, s23
	v_mov_b32_e32 v15, v12
	global_store_dwordx2 v46, v[14:15], s[22:23]
	s_branch .LBB0_1254

; DEV unsigned pk2(float lo, float hi) { f32x2_ v; v.x = lo; v.y = hi; return __builtin_bit_cast(unsigned, __builtin_convertvector(v, bf16x2_)); }
; DEV void ln_rows(float* hbuf, bf16* hb, const float* g, const float* bta, float* stats, bool write_h, int gw, int NGW, int lane) {
;     ...
;             if (lane == 0) { f32x2_ st2; st2.x = mean; st2.y = rstd; *(f32x2_*)(stats + 2 * m) = st2; }
;             f32x4* xr = (f32x4*)(hbuf + (size_t)m * DM) + lane;
;             unsigned long long* o8 = (unsigned long long*)(hb + (size_t)m * DM) + lane;
; #pragma unroll
;             for (int j = 0; j < 4; ++j) { const f32x4 gg = ((const f32x4*)g)[lane + 64 * j], bb = ((const f32x4*)bta)[lane + 64 * j];
;                 const f32x4 o = v[q][j] * rstd * gg + bb; if (write_h) xr[64 * j] = o;
;                 o8[64 * j] = (unsigned long long)pk2(o.x, o.y) | ((unsigned long long)pk2(o.z, o.w) << 32); }
.LBB0_1480:
	s_or_b64 exec, exec, s[0:1]
	s_add_i32 s0, 0, 0x27948
	s_waitcnt lgkmcnt(0)
	v_mov_b32_e32 v0, s0
	s_barrier
	ds_read2_b64 v[0:3], v0 offset1:1
	s_andn2_b64 vcc, exec, s[16:17]
	s_waitcnt lgkmcnt(0)
	v_readfirstlane_b32 s6, v0
	v_readfirstlane_b32 s7, v1
	v_readfirstlane_b32 s8, v2
	v_readfirstlane_b32 s9, v3
	s_cbranch_vccnz .LBB0_1487
	v_ashrrev_i32_e32 v161, 31, v160
	v_lshlrev_b64 v[0:1], 4, v[160:161]
	v_lshlrev_b32_e32 v2, 2, v160
	s_lshl_b32 s4, s2, 4
	s_lshl_b32 s5, s13, 1
	v_lshl_add_u64 v[32:33], s[48:49], 0, v[0:1]
	v_xor_b32_e32 v42, 64, v2
	v_xor_b32_e32 v43, 0x80, v2
	v_cmp_eq_u32_e64 s[0:1], 0, v160
	v_lshl_add_u64 v[34:35], v[160:161], 3, s[70:71]
	v_lshl_add_u64 v[36:37], s[6:7], 0, v[0:1]
	v_lshl_add_u64 v[38:39], s[8:9], 0, v[0:1]
	flat_load_dwordx4 v[64:67], v[36:37]
	flat_load_dwordx4 v[68:71], v[36:37] offset:1024
	flat_load_dwordx4 v[72:75], v[36:37] offset:2048
	flat_load_dwordx4 v[76:79], v[36:37] offset:3072
	flat_load_dwordx4 v[80:83], v[38:39]
	flat_load_dwordx4 v[84:87], v[38:39] offset:1024
	flat_load_dwordx4 v[88:91], v[38:39] offset:2048
	flat_load_dwordx4 v[92:95], v[38:39] offset:3072
	s_waitcnt vmcnt(0) lgkmcnt(0)
	s_add_i32 s8, s4, s5
	s_lshl_b32 s4, s58, 5
	s_lshl_b32 s5, s58, 4
	v_mov_b32_e32 v44, 0x3727c5ac
	s_mov_b32 s14, 0xf800000
	v_mov_b32_e32 v45, 0x260
	v_mov_b32_e32 v46, 0
	s_branch .LBB0_1483
.LBB0_1482:
	s_or_b64 exec, exec, s[6:7]
	v_pk_mul_f32 v[14:15], v[18:19], v[12:13] op_sel_hi:[1,0]
	v_pk_mul_f32 v[16:17], v[16:17], v[12:13] op_sel_hi:[1,0]
	s_lshl_b64 s[6:7], s[16:17], 11
	v_lshl_add_u64 v[28:29], v[34:35], 0, s[6:7]
	v_pk_mul_f32 v[10:11], v[10:11], v[12:13] op_sel_hi:[1,0]
	v_pk_mul_f32 v[8:9], v[8:9], v[12:13] op_sel_hi:[1,0]
	v_pk_mul_f32 v[6:7], v[6:7], v[12:13] op_sel_hi:[1,0]
	v_pk_mul_f32 v[4:5], v[4:5], v[12:13] op_sel_hi:[1,0]
	v_pk_mul_f32 v[2:3], v[2:3], v[12:13] op_sel_hi:[1,0]
	v_pk_mul_f32 v[0:1], v[0:1], v[12:13] op_sel_hi:[1,0]
	s_add_i32 s12, s16, s62
	s_add_i32 s8, s8, s4
	s_cmp_lt_i32 s12, 0x8000
	v_pk_fma_f32 v[14:15], v[14:15], v[66:67], v[82:83]
	v_pk_fma_f32 v[16:17], v[16:17], v[64:65], v[80:81]
	s_nop 0
	v_cvt_pk_bf16_f32 v16, v16, v17
	v_cvt_pk_bf16_f32 v17, v14, v15
	global_store_dwordx2 v[28:29], v[16:17], off
	v_pk_fma_f32 v[10:11], v[10:11], v[70:71], v[86:87]
	v_pk_fma_f32 v[8:9], v[8:9], v[68:69], v[84:85]
	s_nop 0
	v_cvt_pk_bf16_f32 v8, v8, v9
	v_cvt_pk_bf16_f32 v9, v10, v11
	global_store_dwordx2 v[28:29], v[8:9], off offset:512
	v_pk_fma_f32 v[6:7], v[6:7], v[74:75], v[90:91]
	v_pk_fma_f32 v[4:5], v[4:5], v[72:73], v[88:89]
	s_nop 0
	v_cvt_pk_bf16_f32 v4, v4, v5
	v_cvt_pk_bf16_f32 v5, v6, v7
	global_store_dwordx2 v[28:29], v[4:5], off offset:1024
	v_pk_fma_f32 v[2:3], v[2:3], v[78:79], v[94:95]
	v_pk_fma_f32 v[0:1], v[0:1], v[76:77], v[92:93]
	s_nop 0
	v_cvt_pk_bf16_f32 v0, v0, v1
	v_cvt_pk_bf16_f32 v1, v2, v3
	global_store_dwordx2 v[28:29], v[0:1], off offset:1536
	s_cbranch_scc0 .LBB0_1487

; DEV unsigned pk2(float lo, float hi) { f32x2_ v; v.x = lo; v.y = hi; return __builtin_bit_cast(unsigned, __builtin_convertvector(v, bf16x2_)); }
; DEV void ln_rows(float* hbuf, bf16* hb, const float* g, const float* bta, float* stats, bool write_h, int gw, int NGW, int lane) {
;     ...
;         for (int q = 0; q < 2; ++q) {
;             const int m = m0 + q * NGW;
;             const float mean = wave_sum(s[q], lane) * (1.f / DM); float s2 = 0.f;
; #pragma unroll
;             for (int j = 0; j < 4; ++j) { v[q][j] = v[q][j] - mean; s2 += (v[q][j].x * v[q][j].x + v[q][j].y * v[q][j].y) + (v[q][j].z * v[q][j].z + v[q][j].w * v[q][j].w); }
;             const float rstd = 1.f / sqrtf(wave_sum(s2, lane) * (1.f / DM) + 1e-5f);
;             if (lane == 0) { f32x2_ st2; st2.x = mean; st2.y = rstd; *(f32x2_*)(stats + 2 * m) = st2; }
;             f32x4* xr = (f32x4*)(hbuf + (size_t)m * DM) + lane;
;             unsigned long long* o8 = (unsigned long long*)(hb + (size_t)m * DM) + lane;
; #pragma unroll
;             for (int j = 0; j < 4; ++j) { const f32x4 gg = ((const f32x4*)g)[lane + 64 * j], bb = ((const f32x4*)bta)[lane + 64 * j];
;                 const f32x4 o = v[q][j] * rstd * gg + bb; if (write_h) xr[64 * j] = o;
;                 o8[64 * j] = (unsigned long long)pk2(o.x, o.y) | ((unsigned long long)pk2(o.z, o.w) << 32); }
.LBB0_1485:
	s_or_b64 exec, exec, s[6:7]
	v_pk_mul_f32 v[40:41], v[40:41], v[22:23] op_sel_hi:[1,0]
	v_pk_mul_f32 v[28:29], v[28:29], v[22:23] op_sel_hi:[1,0]
	s_lshl_b64 s[6:7], s[12:13], 11
	v_lshl_add_u64 v[56:57], v[34:35], 0, s[6:7]
	v_pk_mul_f32 v[24:25], v[24:25], v[22:23] op_sel_hi:[1,0]
	s_waitcnt vmcnt(1)
	v_add_f32_e32 v47, v6, v7
	s_waitcnt lgkmcnt(0)
	v_pk_fma_f32 v[40:41], v[40:41], v[66:67], v[82:83]
	v_pk_fma_f32 v[28:29], v[28:29], v[64:65], v[80:81]
	s_nop 0
	v_cvt_pk_bf16_f32 v28, v28, v29
	v_cvt_pk_bf16_f32 v29, v40, v41
	global_store_dwordx2 v[56:57], v[28:29], off
	v_pk_mul_f32 v[28:29], v[30:31], v[22:23] op_sel_hi:[1,0]
	v_add_f32_e32 v23, v16, v17
	v_add_f32_e32 v40, v10, v11
	v_add_f32_e32 v41, v4, v5
	v_pk_fma_f32 v[28:29], v[28:29], v[70:71], v[86:87]
	v_pk_fma_f32 v[24:25], v[24:25], v[68:69], v[84:85]
	v_add_f32_e32 v52, v0, v1
	v_cvt_pk_bf16_f32 v24, v24, v25
	v_cvt_pk_bf16_f32 v25, v28, v29
	global_store_dwordx2 v[56:57], v[24:25], off offset:512
	v_add_f32_e32 v24, v18, v19
	v_add_f32_e32 v25, v8, v9
	v_add_f32_e32 v23, v23, v24
	v_add_f32_e32 v24, v25, v40
	v_add_f32_e32 v23, 0, v23
	v_add_f32_e32 v53, v2, v3
	v_add_f32_e32 v25, v41, v47
	v_add_f32_e32 v23, v23, v24
	v_add_f32_e32 v40, v52, v53
	v_add_f32_e32 v23, v23, v25
	v_add_f32_e32 v23, v23, v40
	s_nop 1
	v_add_f32_dpp v23, v23, v23 quad_perm:[1,0,3,2] row_mask:0xf bank_mask:0xf bound_ctrl:1
	s_nop 1
	v_add_f32_dpp v23, v23, v23 quad_perm:[2,3,0,1] row_mask:0xf bank_mask:0xf bound_ctrl:1
	s_nop 1
	v_add_f32_dpp v23, v23, v23 row_half_mirror row_mask:0xf bank_mask:0xf bound_ctrl:1
	s_nop 1
	v_add_f32_dpp v23, v23, v23 row_mirror row_mask:0xf bank_mask:0xf bound_ctrl:1
	ds_bpermute_b32 v24, v42, v23
	s_waitcnt lgkmcnt(0)
	v_add_f32_e32 v23, v23, v24
	v_pk_mul_f32 v[24:25], v[26:27], v[22:23] op_sel_hi:[1,0]
	v_pk_mul_f32 v[26:27], v[20:21], v[22:23] op_sel_hi:[1,0]
	ds_bpermute_b32 v40, v43, v23
	s_waitcnt lgkmcnt(0)
	v_add_f32_e32 v20, v23, v40
	v_fmamk_f32 v19, v20, 0xba800000, v19
	v_fmamk_f32 v17, v20, 0xba800000, v17
	v_fmamk_f32 v11, v20, 0xba800000, v11
	v_fmamk_f32 v9, v20, 0xba800000, v9
	v_fmamk_f32 v18, v20, 0xba800000, v18
	v_fmac_f32_e32 v16, 0xba800000, v20
	v_fmamk_f32 v10, v20, 0xba800000, v10
	v_fmac_f32_e32 v8, 0xba800000, v20
	v_fmamk_f32 v7, v20, 0xba800000, v7
	v_fmamk_f32 v5, v20, 0xba800000, v5
	v_mul_f32_e32 v21, v17, v17
	v_mul_f32_e32 v23, v19, v19
	v_mul_f32_e32 v40, v9, v9
	v_mul_f32_e32 v41, v11, v11
	v_fmamk_f32 v6, v20, 0xba800000, v6
	v_fmac_f32_e32 v4, 0xba800000, v20
	v_fmamk_f32 v3, v20, 0xba800000, v3
	v_fmamk_f32 v1, v20, 0xba800000, v1
	v_mul_f32_e32 v47, v5, v5
	v_fmac_f32_e32 v21, v16, v16
	v_fmac_f32_e32 v23, v18, v18
	v_fmac_f32_e32 v40, v8, v8
	v_fmac_f32_e32 v41, v10, v10
	v_fmamk_f32 v2, v20, 0xba800000, v2
	v_fmac_f32_e32 v0, 0xba800000, v20
	v_fmac_f32_e32 v47, v4, v4
	v_add_f32_e32 v21, v21, v23
	v_add_f32_e32 v23, v40, v41
	v_add_f32_e32 v21, v21, v23
	v_pk_fma_f32 v[24:25], v[24:25], v[74:75], v[90:91]
	v_pk_fma_f32 v[26:27], v[26:27], v[72:73], v[88:89]
	v_mul_f32_e32 v48, v7, v7
	v_cvt_pk_bf16_f32 v26, v26, v27
	v_cvt_pk_bf16_f32 v27, v24, v25
	global_store_dwordx2 v[56:57], v[26:27], off offset:1024
	v_mul_f32_e32 v49, v1, v1
	v_mul_f32_e32 v50, v3, v3
	v_fmac_f32_e32 v48, v6, v6
	v_fmac_f32_e32 v49, v0, v0
	v_fmac_f32_e32 v50, v2, v2
	v_add_f32_e32 v40, v47, v48
	v_add_f32_e32 v41, v49, v50
	v_add_f32_e32 v21, v40, v21
	v_add_f32_e32 v21, v41, v21
	s_nop 1
	v_add_f32_dpp v21, v21, v21 quad_perm:[1,0,3,2] row_mask:0xf bank_mask:0xf bound_ctrl:1
	s_nop 1
	v_add_f32_dpp v21, v21, v21 quad_perm:[2,3,0,1] row_mask:0xf bank_mask:0xf bound_ctrl:1
	s_nop 1
	v_add_f32_dpp v21, v21, v21 row_half_mirror row_mask:0xf bank_mask:0xf bound_ctrl:1
	s_nop 1
	v_add_f32_dpp v21, v21, v21 row_mirror row_mask:0xf bank_mask:0xf bound_ctrl:1
	ds_bpermute_b32 v23, v42, v21
	s_waitcnt lgkmcnt(0)
	v_add_f32_e32 v21, v21, v23
	ds_bpermute_b32 v23, v43, v21
	s_waitcnt lgkmcnt(0)
	v_add_f32_e32 v21, v21, v23
	v_fmamk_f32 v21, v21, 0x3a800000, v44
	v_mul_f32_e32 v23, 0x4f800000, v21
	v_cmp_gt_f32_e32 vcc, s14, v21
	s_nop 1
	v_cndmask_b32_e32 v21, v21, v23, vcc
	v_sqrt_f32_e32 v23, v21
	s_nop 0
	v_add_u32_e32 v40, -1, v23
	v_add_u32_e32 v41, 1, v23
	v_fma_f32 v47, -v40, v23, v21
	v_fma_f32 v48, -v41, v23, v21
	v_cmp_ge_f32_e64 s[6:7], 0, v47
	v_pk_mul_f32 v[14:15], v[14:15], v[22:23] op_sel_hi:[1,0]
	s_nop 0
	v_cndmask_b32_e64 v23, v23, v40, s[6:7]
	v_cmp_lt_f32_e64 s[6:7], 0, v48
	v_pk_fma_f32 v[14:15], v[14:15], v[78:79], v[94:95]
	v_cndmask_b32_e64 v23, v23, v41, s[6:7]
	v_mul_f32_e32 v40, 0x37800000, v23
	v_cndmask_b32_e32 v23, v23, v40, vcc
	v_cmp_class_f32_e32 vcc, v21, v45
	s_nop 1
	v_cndmask_b32_e32 v21, v23, v21, vcc
	v_div_scale_f32 v23, s[6:7], v21, v21, 1.0
	v_rcp_f32_e32 v40, v23
	v_pk_mul_f32 v[12:13], v[12:13], v[22:23] op_sel_hi:[1,0]
	v_div_scale_f32 v22, vcc, 1.0, v21, 1.0
	v_fma_f32 v41, -v23, v40, 1.0
	v_fmac_f32_e32 v40, v41, v40
	v_mul_f32_e32 v41, v22, v40
	v_fma_f32 v47, -v23, v41, v22
	v_fmac_f32_e32 v41, v47, v40
	v_fma_f32 v22, -v23, v41, v22
	v_pk_fma_f32 v[12:13], v[12:13], v[76:77], v[92:93]
	v_div_fmas_f32 v22, v22, v40, v41
	v_cvt_pk_bf16_f32 v12, v12, v13
	v_cvt_pk_bf16_f32 v13, v14, v15
	global_store_dwordx2 v[56:57], v[12:13], off offset:1536
	v_div_fixup_f32 v12, v22, v21, 1.0
	s_and_saveexec_b64 s[6:7], s[0:1]
	s_cbranch_execz .LBB0_1482
	s_add_i32 s12, s5, s8
	s_ashr_i32 s13, s12, 31
	s_lshl_b64 s[12:13], s[12:13], 2
	s_add_u32 s12, s10, s12
	v_mul_f32_e32 v14, 0x3a800000, v20
	s_addc_u32 s13, s11, s13
	v_mov_b32_e32 v15, v12
	global_store_dwordx2 v46, v[14:15], s[12:13]
	s_branch .LBB0_1482

; DEV unsigned pk2(float lo, float hi) { f32x2_ v; v.x = lo; v.y = hi; return __builtin_bit_cast(unsigned, __builtin_convertvector(v, bf16x2_)); }
; DEV void ln_rows(float* hbuf, bf16* hb, const float* g, const float* bta, float* stats, bool write_h, int gw, int NGW, int lane) {
;     ...
;             if (lane == 0) { f32x2_ st2; st2.x = mean; st2.y = rstd; *(f32x2_*)(stats + 2 * m) = st2; }
;             f32x4* xr = (f32x4*)(hbuf + (size_t)m * DM) + lane;
;             unsigned long long* o8 = (unsigned long long*)(hb + (size_t)m * DM) + lane;
; #pragma unroll
;             for (int j = 0; j < 4; ++j) { const f32x4 gg = ((const f32x4*)g)[lane + 64 * j], bb = ((const f32x4*)bta)[lane + 64 * j];
;                 const f32x4 o = v[q][j] * rstd * gg + bb; if (write_h) xr[64 * j] = o;
;                 o8[64 * j] = (unsigned long long)pk2(o.x, o.y) | ((unsigned long long)pk2(o.z, o.w) << 32); }
.LBB0_2007:
	s_or_b64 exec, exec, s[0:1]
	s_add_u32 s24, s50, 0x600000
	s_addc_u32 s25, s51, 0
	s_add_i32 s0, 0, 0x27988
	s_waitcnt lgkmcnt(0)
	v_mov_b32_e32 v0, s0
	s_barrier
	ds_read2_b64 v[0:3], v0 offset1:1
	s_andn2_b64 vcc, exec, s[12:13]
	s_waitcnt lgkmcnt(0)
	v_readfirstlane_b32 s11, v1
	v_cndmask_b32_e64 v1, 0, 1, s[12:13]
	v_readfirstlane_b32 s10, v0
	v_readfirstlane_b32 s26, v2
	v_readfirstlane_b32 s27, v3
	v_mov_b32_e32 v0, v160
	v_cmp_ne_u32_e64 s[8:9], 1, v1
	s_cbranch_vccnz .LBB0_2014
	v_ashrrev_i32_e32 v1, 31, v0
	v_lshlrev_b64 v[2:3], 4, v[0:1]
	v_lshlrev_b32_e32 v4, 2, v0
	s_lshl_b32 s4, s2, 4
	s_lshl_b32 s5, s66, 1
	v_lshl_add_u64 v[32:33], s[48:49], 0, v[2:3]
	v_xor_b32_e32 v42, 64, v4
	v_xor_b32_e32 v43, 0x80, v4
	v_cmp_eq_u32_e64 s[0:1], 0, v0
	v_lshl_add_u64 v[34:35], v[0:1], 3, s[16:17]
	v_lshl_add_u64 v[36:37], s[10:11], 0, v[2:3]
	v_lshl_add_u64 v[38:39], s[26:27], 0, v[2:3]
	flat_load_dwordx4 v[64:67], v[36:37]
	flat_load_dwordx4 v[68:71], v[36:37] offset:1024
	flat_load_dwordx4 v[72:75], v[36:37] offset:2048
	flat_load_dwordx4 v[76:79], v[36:37] offset:3072
	flat_load_dwordx4 v[80:83], v[38:39]
	flat_load_dwordx4 v[84:87], v[38:39] offset:1024
	flat_load_dwordx4 v[88:91], v[38:39] offset:2048
	flat_load_dwordx4 v[92:95], v[38:39] offset:3072
	s_waitcnt vmcnt(0) lgkmcnt(0)
	s_add_i32 s12, s4, s5
	s_lshl_b32 s4, s58, 5
	s_lshl_b32 s5, s58, 4
	v_mov_b32_e32 v44, 0x3727c5ac
	s_mov_b32 s14, 0xf800000
	v_mov_b32_e32 v45, 0x260
	v_mov_b32_e32 v46, 0
	s_mov_b32 s28, s20
	s_branch .LBB0_2010
.LBB0_2009:
	s_or_b64 exec, exec, s[10:11]
	v_pk_mul_f32 v[14:15], v[18:19], v[12:13] op_sel_hi:[1,0]
	v_pk_mul_f32 v[16:17], v[16:17], v[12:13] op_sel_hi:[1,0]
	s_lshl_b64 s[10:11], s[26:27], 11
	v_lshl_add_u64 v[28:29], v[34:35], 0, s[10:11]
	v_pk_mul_f32 v[10:11], v[10:11], v[12:13] op_sel_hi:[1,0]
	v_pk_mul_f32 v[8:9], v[8:9], v[12:13] op_sel_hi:[1,0]
	v_pk_mul_f32 v[6:7], v[6:7], v[12:13] op_sel_hi:[1,0]
	v_pk_mul_f32 v[4:5], v[4:5], v[12:13] op_sel_hi:[1,0]
	v_pk_mul_f32 v[2:3], v[2:3], v[12:13] op_sel_hi:[1,0]
	v_pk_mul_f32 v[0:1], v[0:1], v[12:13] op_sel_hi:[1,0]
	s_add_i32 s28, s26, s62
	s_add_i32 s12, s12, s4
	s_cmp_lt_i32 s28, 0x8000
	v_pk_fma_f32 v[14:15], v[14:15], v[66:67], v[82:83]
	v_pk_fma_f32 v[16:17], v[16:17], v[64:65], v[80:81]
	s_nop 0
	v_cvt_pk_bf16_f32 v16, v16, v17
	v_cvt_pk_bf16_f32 v17, v14, v15
	global_store_dwordx2 v[28:29], v[16:17], off
	v_pk_fma_f32 v[10:11], v[10:11], v[70:71], v[86:87]
	v_pk_fma_f32 v[8:9], v[8:9], v[68:69], v[84:85]
	s_nop 0
	v_cvt_pk_bf16_f32 v8, v8, v9
	v_cvt_pk_bf16_f32 v9, v10, v11
	global_store_dwordx2 v[28:29], v[8:9], off offset:512
	v_pk_fma_f32 v[6:7], v[6:7], v[74:75], v[90:91]
	v_pk_fma_f32 v[4:5], v[4:5], v[72:73], v[88:89]
	s_nop 0
	v_cvt_pk_bf16_f32 v4, v4, v5
	v_cvt_pk_bf16_f32 v5, v6, v7
	global_store_dwordx2 v[28:29], v[4:5], off offset:1024
	v_pk_fma_f32 v[2:3], v[2:3], v[78:79], v[94:95]
	v_pk_fma_f32 v[0:1], v[0:1], v[76:77], v[92:93]
	s_nop 0
	v_cvt_pk_bf16_f32 v0, v0, v1
	v_cvt_pk_bf16_f32 v1, v2, v3
	global_store_dwordx2 v[28:29], v[0:1], off offset:1536
	s_cbranch_scc0 .LBB0_2014

; DEV unsigned pk2(float lo, float hi) { f32x2_ v; v.x = lo; v.y = hi; return __builtin_bit_cast(unsigned, __builtin_convertvector(v, bf16x2_)); }
; DEV void ln_rows(float* hbuf, bf16* hb, const float* g, const float* bta, float* stats, bool write_h, int gw, int NGW, int lane) {
;     ...
;         for (int q = 0; q < 2; ++q) {
;             const int m = m0 + q * NGW;
;             const float mean = wave_sum(s[q], lane) * (1.f / DM); float s2 = 0.f;
; #pragma unroll
;             for (int j = 0; j < 4; ++j) { v[q][j] = v[q][j] - mean; s2 += (v[q][j].x * v[q][j].x + v[q][j].y * v[q][j].y) + (v[q][j].z * v[q][j].z + v[q][j].w * v[q][j].w); }
;             const float rstd = 1.f / sqrtf(wave_sum(s2, lane) * (1.f / DM) + 1e-5f);
;             if (lane == 0) { f32x2_ st2; st2.x = mean; st2.y = rstd; *(f32x2_*)(stats + 2 * m) = st2; }
;             f32x4* xr = (f32x4*)(hbuf + (size_t)m * DM) + lane;
;             unsigned long long* o8 = (unsigned long long*)(hb + (size_t)m * DM) + lane;
; #pragma unroll
;             for (int j = 0; j < 4; ++j) { const f32x4 gg = ((const f32x4*)g)[lane + 64 * j], bb = ((const f32x4*)bta)[lane + 64 * j];
;                 const f32x4 o = v[q][j] * rstd * gg + bb; if (write_h) xr[64 * j] = o;
;                 o8[64 * j] = (unsigned long long)pk2(o.x, o.y) | ((unsigned long long)pk2(o.z, o.w) << 32); }
.LBB0_2012:
	s_or_b64 exec, exec, s[10:11]
	v_pk_mul_f32 v[40:41], v[40:41], v[22:23] op_sel_hi:[1,0]
	v_pk_mul_f32 v[28:29], v[28:29], v[22:23] op_sel_hi:[1,0]
	s_lshl_b64 s[10:11], s[28:29], 11
	v_lshl_add_u64 v[56:57], v[34:35], 0, s[10:11]
	v_pk_mul_f32 v[24:25], v[24:25], v[22:23] op_sel_hi:[1,0]
	s_waitcnt vmcnt(1)
	v_add_f32_e32 v47, v6, v7
	s_waitcnt lgkmcnt(0)
	v_pk_fma_f32 v[40:41], v[40:41], v[66:67], v[82:83]
	v_pk_fma_f32 v[28:29], v[28:29], v[64:65], v[80:81]
	s_nop 0
	v_cvt_pk_bf16_f32 v28, v28, v29
	v_cvt_pk_bf16_f32 v29, v40, v41
	global_store_dwordx2 v[56:57], v[28:29], off
	v_pk_mul_f32 v[28:29], v[30:31], v[22:23] op_sel_hi:[1,0]
	v_add_f32_e32 v23, v16, v17
	v_add_f32_e32 v40, v10, v11
	v_add_f32_e32 v41, v4, v5
	v_pk_fma_f32 v[28:29], v[28:29], v[70:71], v[86:87]
	v_pk_fma_f32 v[24:25], v[24:25], v[68:69], v[84:85]
	v_add_f32_e32 v52, v0, v1
	v_cvt_pk_bf16_f32 v24, v24, v25
	v_cvt_pk_bf16_f32 v25, v28, v29
	global_store_dwordx2 v[56:57], v[24:25], off offset:512
	v_add_f32_e32 v24, v18, v19
	v_add_f32_e32 v25, v8, v9
	v_add_f32_e32 v23, v23, v24
	v_add_f32_e32 v24, v25, v40
	v_add_f32_e32 v23, 0, v23
	v_add_f32_e32 v53, v2, v3
	v_add_f32_e32 v25, v41, v47
	v_add_f32_e32 v23, v23, v24
	v_add_f32_e32 v40, v52, v53
	v_add_f32_e32 v23, v23, v25
	v_add_f32_e32 v23, v23, v40
	s_nop 1
	v_add_f32_dpp v23, v23, v23 quad_perm:[1,0,3,2] row_mask:0xf bank_mask:0xf bound_ctrl:1
	s_nop 1
	v_add_f32_dpp v23, v23, v23 quad_perm:[2,3,0,1] row_mask:0xf bank_mask:0xf bound_ctrl:1
	s_nop 1
	v_add_f32_dpp v23, v23, v23 row_half_mirror row_mask:0xf bank_mask:0xf bound_ctrl:1
	s_nop 1
	v_add_f32_dpp v23, v23, v23 row_mirror row_mask:0xf bank_mask:0xf bound_ctrl:1
	ds_bpermute_b32 v24, v42, v23
	s_waitcnt lgkmcnt(0)
	v_add_f32_e32 v23, v23, v24
	v_pk_mul_f32 v[24:25], v[26:27], v[22:23] op_sel_hi:[1,0]
	v_pk_mul_f32 v[26:27], v[20:21], v[22:23] op_sel_hi:[1,0]
	ds_bpermute_b32 v40, v43, v23
	s_waitcnt lgkmcnt(0)
	v_add_f32_e32 v20, v23, v40
	v_fmamk_f32 v19, v20, 0xba800000, v19
	v_fmamk_f32 v17, v20, 0xba800000, v17
	v_fmamk_f32 v11, v20, 0xba800000, v11
	v_fmamk_f32 v9, v20, 0xba800000, v9
	v_fmamk_f32 v18, v20, 0xba800000, v18
	v_fmac_f32_e32 v16, 0xba800000, v20
	v_fmamk_f32 v10, v20, 0xba800000, v10
	v_fmac_f32_e32 v8, 0xba800000, v20
	v_fmamk_f32 v7, v20, 0xba800000, v7
	v_fmamk_f32 v5, v20, 0xba800000, v5
	v_mul_f32_e32 v21, v17, v17
	v_mul_f32_e32 v23, v19, v19
	v_mul_f32_e32 v40, v9, v9
	v_mul_f32_e32 v41, v11, v11
	v_fmamk_f32 v6, v20, 0xba800000, v6
	v_fmac_f32_e32 v4, 0xba800000, v20
	v_fmamk_f32 v3, v20, 0xba800000, v3
	v_fmamk_f32 v1, v20, 0xba800000, v1
	v_mul_f32_e32 v47, v5, v5
	v_fmac_f32_e32 v21, v16, v16
	v_fmac_f32_e32 v23, v18, v18
	v_fmac_f32_e32 v40, v8, v8
	v_fmac_f32_e32 v41, v10, v10
	v_fmamk_f32 v2, v20, 0xba800000, v2
	v_fmac_f32_e32 v0, 0xba800000, v20
	v_fmac_f32_e32 v47, v4, v4
	v_add_f32_e32 v21, v21, v23
	v_add_f32_e32 v23, v40, v41
	v_add_f32_e32 v21, v21, v23
	v_pk_fma_f32 v[24:25], v[24:25], v[74:75], v[90:91]
	v_pk_fma_f32 v[26:27], v[26:27], v[72:73], v[88:89]
	v_mul_f32_e32 v48, v7, v7
	v_cvt_pk_bf16_f32 v26, v26, v27
	v_cvt_pk_bf16_f32 v27, v24, v25
	global_store_dwordx2 v[56:57], v[26:27], off offset:1024
	v_mul_f32_e32 v49, v1, v1
	v_mul_f32_e32 v50, v3, v3
	v_fmac_f32_e32 v48, v6, v6
	v_fmac_f32_e32 v49, v0, v0
	v_fmac_f32_e32 v50, v2, v2
	v_add_f32_e32 v40, v47, v48
	v_add_f32_e32 v41, v49, v50
	v_add_f32_e32 v21, v40, v21
	v_add_f32_e32 v21, v41, v21
	s_nop 1
	v_add_f32_dpp v21, v21, v21 quad_perm:[1,0,3,2] row_mask:0xf bank_mask:0xf bound_ctrl:1
	s_nop 1
	v_add_f32_dpp v21, v21, v21 quad_perm:[2,3,0,1] row_mask:0xf bank_mask:0xf bound_ctrl:1
	s_nop 1
	v_add_f32_dpp v21, v21, v21 row_half_mirror row_mask:0xf bank_mask:0xf bound_ctrl:1
	s_nop 1
	v_add_f32_dpp v21, v21, v21 row_mirror row_mask:0xf bank_mask:0xf bound_ctrl:1
	ds_bpermute_b32 v23, v42, v21
	s_waitcnt lgkmcnt(0)
	v_add_f32_e32 v21, v21, v23
	ds_bpermute_b32 v23, v43, v21
	s_waitcnt lgkmcnt(0)
	v_add_f32_e32 v21, v21, v23
	v_fmamk_f32 v21, v21, 0x3a800000, v44
	v_mul_f32_e32 v23, 0x4f800000, v21
	v_cmp_gt_f32_e32 vcc, s14, v21
	s_nop 1
	v_cndmask_b32_e32 v21, v21, v23, vcc
	v_sqrt_f32_e32 v23, v21
	s_nop 0
	v_add_u32_e32 v40, -1, v23
	v_add_u32_e32 v41, 1, v23
	v_fma_f32 v47, -v40, v23, v21
	v_fma_f32 v48, -v41, v23, v21
	v_cmp_ge_f32_e64 s[10:11], 0, v47
	v_pk_mul_f32 v[14:15], v[14:15], v[22:23] op_sel_hi:[1,0]
	s_nop 0
	v_cndmask_b32_e64 v23, v23, v40, s[10:11]
	v_cmp_lt_f32_e64 s[10:11], 0, v48
	v_pk_fma_f32 v[14:15], v[14:15], v[78:79], v[94:95]
	v_cndmask_b32_e64 v23, v23, v41, s[10:11]
	v_mul_f32_e32 v40, 0x37800000, v23
	v_cndmask_b32_e32 v23, v23, v40, vcc
	v_cmp_class_f32_e32 vcc, v21, v45
	s_nop 1
	v_cndmask_b32_e32 v21, v23, v21, vcc
	v_div_scale_f32 v23, s[10:11], v21, v21, 1.0
	v_rcp_f32_e32 v40, v23
	v_pk_mul_f32 v[12:13], v[12:13], v[22:23] op_sel_hi:[1,0]
	v_div_scale_f32 v22, vcc, 1.0, v21, 1.0
	v_fma_f32 v41, -v23, v40, 1.0
	v_fmac_f32_e32 v40, v41, v40
	v_mul_f32_e32 v41, v22, v40
	v_fma_f32 v47, -v23, v41, v22
	v_fmac_f32_e32 v41, v47, v40
	v_fma_f32 v22, -v23, v41, v22
	v_pk_fma_f32 v[12:13], v[12:13], v[76:77], v[92:93]
	v_div_fmas_f32 v22, v22, v40, v41
	v_cvt_pk_bf16_f32 v12, v12, v13
	v_cvt_pk_bf16_f32 v13, v14, v15
	global_store_dwordx2 v[56:57], v[12:13], off offset:1536
	v_div_fixup_f32 v12, v22, v21, 1.0
	s_and_saveexec_b64 s[10:11], s[0:1]
	s_cbranch_execz .LBB0_2009
	s_add_i32 s28, s5, s12
	s_ashr_i32 s29, s28, 31
	s_lshl_b64 s[28:29], s[28:29], 2
	s_add_u32 s28, s24, s28
	v_mul_f32_e32 v14, 0x3a800000, v20
	s_addc_u32 s29, s25, s29
	v_mov_b32_e32 v15, v12
	global_store_dwordx2 v46, v[14:15], s[28:29]
	s_branch .LBB0_2009

; DEV unsigned pk2(float lo, float hi) { f32x2_ v; v.x = lo; v.y = hi; return __builtin_bit_cast(unsigned, __builtin_convertvector(v, bf16x2_)); }
; DEV void ln_rows(float* hbuf, bf16* hb, const float* g, const float* bta, float* stats, bool write_h, int gw, int NGW, int lane) {
;     ...
;             if (lane == 0) { f32x2_ st2; st2.x = mean; st2.y = rstd; *(f32x2_*)(stats + 2 * m) = st2; }
;             f32x4* xr = (f32x4*)(hbuf + (size_t)m * DM) + lane;
;             unsigned long long* o8 = (unsigned long long*)(hb + (size_t)m * DM) + lane;
; #pragma unroll
;             for (int j = 0; j < 4; ++j) { const f32x4 gg = ((const f32x4*)g)[lane + 64 * j], bb = ((const f32x4*)bta)[lane + 64 * j];
;                 const f32x4 o = v[q][j] * rstd * gg + bb; if (write_h) xr[64 * j] = o;
;                 o8[64 * j] = (unsigned long long)pk2(o.x, o.y) | ((unsigned long long)pk2(o.z, o.w) << 32); }
.LBB0_2235:
	s_or_b64 exec, exec, s[0:1]
	s_add_i32 s0, 0, 0x279a8
	s_waitcnt lgkmcnt(0)
	v_mov_b32_e32 v0, s0
	s_barrier
	ds_read2_b64 v[0:3], v0 offset1:1
	s_and_b64 vcc, exec, s[8:9]
	s_waitcnt lgkmcnt(0)
	v_readfirstlane_b32 s10, v0
	v_readfirstlane_b32 s11, v1
	v_readfirstlane_b32 s12, v2
	v_readfirstlane_b32 s13, v3
	s_cbranch_vccnz .LBB0_2242
	v_ashrrev_i32_e32 v161, 31, v160
	v_lshlrev_b64 v[0:1], 4, v[160:161]
	v_lshlrev_b32_e32 v2, 2, v160
	s_lshl_b32 s4, s2, 4
	s_lshl_b32 s5, s66, 1
	v_lshl_add_u64 v[32:33], s[48:49], 0, v[0:1]
	v_xor_b32_e32 v42, 64, v2
	v_xor_b32_e32 v43, 0x80, v2
	v_cmp_eq_u32_e64 s[0:1], 0, v160
	v_lshl_add_u64 v[34:35], v[160:161], 3, s[16:17]
	v_lshl_add_u64 v[36:37], s[10:11], 0, v[0:1]
	v_lshl_add_u64 v[38:39], s[12:13], 0, v[0:1]
	flat_load_dwordx4 v[64:67], v[36:37]
	flat_load_dwordx4 v[68:71], v[36:37] offset:1024
	flat_load_dwordx4 v[72:75], v[36:37] offset:2048
	flat_load_dwordx4 v[76:79], v[36:37] offset:3072
	flat_load_dwordx4 v[80:83], v[38:39]
	flat_load_dwordx4 v[84:87], v[38:39] offset:1024
	flat_load_dwordx4 v[88:91], v[38:39] offset:2048
	flat_load_dwordx4 v[92:95], v[38:39] offset:3072
	s_waitcnt vmcnt(0) lgkmcnt(0)
	s_add_i32 s10, s4, s5
	s_lshl_b32 s4, s58, 5
	s_lshl_b32 s5, s58, 4
	v_mov_b32_e32 v44, 0x3727c5ac
	s_mov_b32 s14, 0xf800000
	v_mov_b32_e32 v45, 0x260
	v_mov_b32_e32 v46, 0
	s_branch .LBB0_2238
.LBB0_2237:
	s_or_b64 exec, exec, s[8:9]
	v_pk_mul_f32 v[14:15], v[18:19], v[12:13] op_sel_hi:[1,0]
	v_pk_mul_f32 v[16:17], v[16:17], v[12:13] op_sel_hi:[1,0]
	s_lshl_b64 s[8:9], s[12:13], 11
	v_lshl_add_u64 v[28:29], v[34:35], 0, s[8:9]
	v_pk_mul_f32 v[10:11], v[10:11], v[12:13] op_sel_hi:[1,0]
	v_pk_mul_f32 v[8:9], v[8:9], v[12:13] op_sel_hi:[1,0]
	v_pk_mul_f32 v[6:7], v[6:7], v[12:13] op_sel_hi:[1,0]
	v_pk_mul_f32 v[4:5], v[4:5], v[12:13] op_sel_hi:[1,0]
	v_pk_mul_f32 v[2:3], v[2:3], v[12:13] op_sel_hi:[1,0]
	v_pk_mul_f32 v[0:1], v[0:1], v[12:13] op_sel_hi:[1,0]
	s_add_i32 s20, s12, s62
	s_add_i32 s10, s10, s4
	s_cmp_lt_i32 s20, 0x8000
	v_pk_fma_f32 v[14:15], v[14:15], v[66:67], v[82:83]
	v_pk_fma_f32 v[16:17], v[16:17], v[64:65], v[80:81]
	s_nop 0
	v_cvt_pk_bf16_f32 v16, v16, v17
	v_cvt_pk_bf16_f32 v17, v14, v15
	global_store_dwordx2 v[28:29], v[16:17], off
	v_pk_fma_f32 v[10:11], v[10:11], v[70:71], v[86:87]
	v_pk_fma_f32 v[8:9], v[8:9], v[68:69], v[84:85]
	s_nop 0
	v_cvt_pk_bf16_f32 v8, v8, v9
	v_cvt_pk_bf16_f32 v9, v10, v11
	global_store_dwordx2 v[28:29], v[8:9], off offset:512
	v_pk_fma_f32 v[6:7], v[6:7], v[74:75], v[90:91]
	v_pk_fma_f32 v[4:5], v[4:5], v[72:73], v[88:89]
	s_nop 0
	v_cvt_pk_bf16_f32 v4, v4, v5
	v_cvt_pk_bf16_f32 v5, v6, v7
	global_store_dwordx2 v[28:29], v[4:5], off offset:1024
	v_pk_fma_f32 v[2:3], v[2:3], v[78:79], v[94:95]
	v_pk_fma_f32 v[0:1], v[0:1], v[76:77], v[92:93]
	s_nop 0
	v_cvt_pk_bf16_f32 v0, v0, v1
	v_cvt_pk_bf16_f32 v1, v2, v3
	global_store_dwordx2 v[28:29], v[0:1], off offset:1536
	s_cbranch_scc0 .LBB0_2242

; DEV unsigned pk2(float lo, float hi) { f32x2_ v; v.x = lo; v.y = hi; return __builtin_bit_cast(unsigned, __builtin_convertvector(v, bf16x2_)); }
; DEV void ln_rows(float* hbuf, bf16* hb, const float* g, const float* bta, float* stats, bool write_h, int gw, int NGW, int lane) {
;     ...
;         for (int q = 0; q < 2; ++q) {
;             const int m = m0 + q * NGW;
;             const float mean = wave_sum(s[q], lane) * (1.f / DM); float s2 = 0.f;
; #pragma unroll
;             for (int j = 0; j < 4; ++j) { v[q][j] = v[q][j] - mean; s2 += (v[q][j].x * v[q][j].x + v[q][j].y * v[q][j].y) + (v[q][j].z * v[q][j].z + v[q][j].w * v[q][j].w); }
;             const float rstd = 1.f / sqrtf(wave_sum(s2, lane) * (1.f / DM) + 1e-5f);
;             if (lane == 0) { f32x2_ st2; st2.x = mean; st2.y = rstd; *(f32x2_*)(stats + 2 * m) = st2; }
;             f32x4* xr = (f32x4*)(hbuf + (size_t)m * DM) + lane;
;             unsigned long long* o8 = (unsigned long long*)(hb + (size_t)m * DM) + lane;
; #pragma unroll
;             for (int j = 0; j < 4; ++j) { const f32x4 gg = ((const f32x4*)g)[lane + 64 * j], bb = ((const f32x4*)bta)[lane + 64 * j];
;                 const f32x4 o = v[q][j] * rstd * gg + bb; if (write_h) xr[64 * j] = o;
;                 o8[64 * j] = (unsigned long long)pk2(o.x, o.y) | ((unsigned long long)pk2(o.z, o.w) << 32); }
.LBB0_2240:
	s_or_b64 exec, exec, s[8:9]
	v_pk_mul_f32 v[40:41], v[40:41], v[22:23] op_sel_hi:[1,0]
	v_pk_mul_f32 v[28:29], v[28:29], v[22:23] op_sel_hi:[1,0]
	s_lshl_b64 s[8:9], s[20:21], 11
	v_lshl_add_u64 v[56:57], v[34:35], 0, s[8:9]
	v_pk_mul_f32 v[24:25], v[24:25], v[22:23] op_sel_hi:[1,0]
	s_waitcnt vmcnt(1)
	v_add_f32_e32 v47, v6, v7
	s_waitcnt lgkmcnt(0)
	v_pk_fma_f32 v[40:41], v[40:41], v[66:67], v[82:83]
	v_pk_fma_f32 v[28:29], v[28:29], v[64:65], v[80:81]
	s_nop 0
	v_cvt_pk_bf16_f32 v28, v28, v29
	v_cvt_pk_bf16_f32 v29, v40, v41
	global_store_dwordx2 v[56:57], v[28:29], off
	v_pk_mul_f32 v[28:29], v[30:31], v[22:23] op_sel_hi:[1,0]
	v_add_f32_e32 v23, v16, v17
	v_add_f32_e32 v40, v10, v11
	v_add_f32_e32 v41, v4, v5
	v_pk_fma_f32 v[28:29], v[28:29], v[70:71], v[86:87]
	v_pk_fma_f32 v[24:25], v[24:25], v[68:69], v[84:85]
	v_add_f32_e32 v52, v0, v1
	v_cvt_pk_bf16_f32 v24, v24, v25
	v_cvt_pk_bf16_f32 v25, v28, v29
	global_store_dwordx2 v[56:57], v[24:25], off offset:512
	v_add_f32_e32 v24, v18, v19
	v_add_f32_e32 v25, v8, v9
	v_add_f32_e32 v23, v23, v24
	v_add_f32_e32 v24, v25, v40
	v_add_f32_e32 v23, 0, v23
	v_add_f32_e32 v53, v2, v3
	v_add_f32_e32 v25, v41, v47
	v_add_f32_e32 v23, v23, v24
	v_add_f32_e32 v40, v52, v53
	v_add_f32_e32 v23, v23, v25
	v_add_f32_e32 v23, v23, v40
	s_nop 1
	v_add_f32_dpp v23, v23, v23 quad_perm:[1,0,3,2] row_mask:0xf bank_mask:0xf bound_ctrl:1
	s_nop 1
	v_add_f32_dpp v23, v23, v23 quad_perm:[2,3,0,1] row_mask:0xf bank_mask:0xf bound_ctrl:1
	s_nop 1
	v_add_f32_dpp v23, v23, v23 row_half_mirror row_mask:0xf bank_mask:0xf bound_ctrl:1
	s_nop 1
	v_add_f32_dpp v23, v23, v23 row_mirror row_mask:0xf bank_mask:0xf bound_ctrl:1
	ds_bpermute_b32 v24, v42, v23
	s_waitcnt lgkmcnt(0)
	v_add_f32_e32 v23, v23, v24
	v_pk_mul_f32 v[24:25], v[26:27], v[22:23] op_sel_hi:[1,0]
	v_pk_mul_f32 v[26:27], v[20:21], v[22:23] op_sel_hi:[1,0]
	ds_bpermute_b32 v40, v43, v23
	s_waitcnt lgkmcnt(0)
	v_add_f32_e32 v20, v23, v40
	v_fmamk_f32 v19, v20, 0xba800000, v19
	v_fmamk_f32 v17, v20, 0xba800000, v17
	v_fmamk_f32 v11, v20, 0xba800000, v11
	v_fmamk_f32 v9, v20, 0xba800000, v9
	v_fmamk_f32 v18, v20, 0xba800000, v18
	v_fmac_f32_e32 v16, 0xba800000, v20
	v_fmamk_f32 v10, v20, 0xba800000, v10
	v_fmac_f32_e32 v8, 0xba800000, v20
	v_fmamk_f32 v7, v20, 0xba800000, v7
	v_fmamk_f32 v5, v20, 0xba800000, v5
	v_mul_f32_e32 v21, v17, v17
	v_mul_f32_e32 v23, v19, v19
	v_mul_f32_e32 v40, v9, v9
	v_mul_f32_e32 v41, v11, v11
	v_fmamk_f32 v6, v20, 0xba800000, v6
	v_fmac_f32_e32 v4, 0xba800000, v20
	v_fmamk_f32 v3, v20, 0xba800000, v3
	v_fmamk_f32 v1, v20, 0xba800000, v1
	v_mul_f32_e32 v47, v5, v5
	v_fmac_f32_e32 v21, v16, v16
	v_fmac_f32_e32 v23, v18, v18
	v_fmac_f32_e32 v40, v8, v8
	v_fmac_f32_e32 v41, v10, v10
	v_fmamk_f32 v2, v20, 0xba800000, v2
	v_fmac_f32_e32 v0, 0xba800000, v20
	v_fmac_f32_e32 v47, v4, v4
	v_add_f32_e32 v21, v21, v23
	v_add_f32_e32 v23, v40, v41
	v_add_f32_e32 v21, v21, v23
	v_pk_fma_f32 v[24:25], v[24:25], v[74:75], v[90:91]
	v_pk_fma_f32 v[26:27], v[26:27], v[72:73], v[88:89]
	v_mul_f32_e32 v48, v7, v7
	v_cvt_pk_bf16_f32 v26, v26, v27
	v_cvt_pk_bf16_f32 v27, v24, v25
	global_store_dwordx2 v[56:57], v[26:27], off offset:1024
	v_mul_f32_e32 v49, v1, v1
	v_mul_f32_e32 v50, v3, v3
	v_fmac_f32_e32 v48, v6, v6
	v_fmac_f32_e32 v49, v0, v0
	v_fmac_f32_e32 v50, v2, v2
	v_add_f32_e32 v40, v47, v48
	v_add_f32_e32 v41, v49, v50
	v_add_f32_e32 v21, v40, v21
	v_add_f32_e32 v21, v41, v21
	s_nop 1
	v_add_f32_dpp v21, v21, v21 quad_perm:[1,0,3,2] row_mask:0xf bank_mask:0xf bound_ctrl:1
	s_nop 1
	v_add_f32_dpp v21, v21, v21 quad_perm:[2,3,0,1] row_mask:0xf bank_mask:0xf bound_ctrl:1
	s_nop 1
	v_add_f32_dpp v21, v21, v21 row_half_mirror row_mask:0xf bank_mask:0xf bound_ctrl:1
	s_nop 1
	v_add_f32_dpp v21, v21, v21 row_mirror row_mask:0xf bank_mask:0xf bound_ctrl:1
	ds_bpermute_b32 v23, v42, v21
	s_waitcnt lgkmcnt(0)
	v_add_f32_e32 v21, v21, v23
	ds_bpermute_b32 v23, v43, v21
	s_waitcnt lgkmcnt(0)
	v_add_f32_e32 v21, v21, v23
	v_fmamk_f32 v21, v21, 0x3a800000, v44
	v_mul_f32_e32 v23, 0x4f800000, v21
	v_cmp_gt_f32_e32 vcc, s14, v21
	s_nop 1
	v_cndmask_b32_e32 v21, v21, v23, vcc
	v_sqrt_f32_e32 v23, v21
	s_nop 0
	v_add_u32_e32 v40, -1, v23
	v_add_u32_e32 v41, 1, v23
	v_fma_f32 v47, -v40, v23, v21
	v_fma_f32 v48, -v41, v23, v21
	v_cmp_ge_f32_e64 s[8:9], 0, v47
	v_pk_mul_f32 v[14:15], v[14:15], v[22:23] op_sel_hi:[1,0]
	s_nop 0
	v_cndmask_b32_e64 v23, v23, v40, s[8:9]
	v_cmp_lt_f32_e64 s[8:9], 0, v48
	v_pk_fma_f32 v[14:15], v[14:15], v[78:79], v[94:95]
	v_cndmask_b32_e64 v23, v23, v41, s[8:9]
	v_mul_f32_e32 v40, 0x37800000, v23
	v_cndmask_b32_e32 v23, v23, v40, vcc
	v_cmp_class_f32_e32 vcc, v21, v45
	s_nop 1
	v_cndmask_b32_e32 v21, v23, v21, vcc
	v_div_scale_f32 v23, s[8:9], v21, v21, 1.0
	v_rcp_f32_e32 v40, v23
	v_pk_mul_f32 v[12:13], v[12:13], v[22:23] op_sel_hi:[1,0]
	v_div_scale_f32 v22, vcc, 1.0, v21, 1.0
	v_fma_f32 v41, -v23, v40, 1.0
	v_fmac_f32_e32 v40, v41, v40
	v_mul_f32_e32 v41, v22, v40
	v_fma_f32 v47, -v23, v41, v22
	v_fmac_f32_e32 v41, v47, v40
	v_fma_f32 v22, -v23, v41, v22
	v_pk_fma_f32 v[12:13], v[12:13], v[76:77], v[92:93]
	v_div_fmas_f32 v22, v22, v40, v41
	v_cvt_pk_bf16_f32 v12, v12, v13
	v_cvt_pk_bf16_f32 v13, v14, v15
	global_store_dwordx2 v[56:57], v[12:13], off offset:1536
	v_div_fixup_f32 v12, v22, v21, 1.0
	s_and_saveexec_b64 s[8:9], s[0:1]
	s_cbranch_execz .LBB0_2237
	s_add_i32 s16, s5, s10
	s_ashr_i32 s17, s16, 31
	s_lshl_b64 s[16:17], s[16:17], 2
	s_add_u32 s16, s22, s16
	v_mul_f32_e32 v14, 0x3a800000, v20
	s_addc_u32 s17, s23, s17
	v_mov_b32_e32 v15, v12
	global_store_dwordx2 v46, v[14:15], s[16:17]
	s_branch .LBB0_2237

; DEV unsigned pk2(float lo, float hi) { f32x2_ v; v.x = lo; v.y = hi; return __builtin_bit_cast(unsigned, __builtin_convertvector(v, bf16x2_)); }
; DEV void ln_rows(float* hbuf, bf16* hb, const float* g, const float* bta, float* stats, bool write_h, int gw, int NGW, int lane) {
;     ...
;             if (lane == 0) { f32x2_ st2; st2.x = mean; st2.y = rstd; *(f32x2_*)(stats + 2 * m) = st2; }
;             f32x4* xr = (f32x4*)(hbuf + (size_t)m * DM) + lane;
;             unsigned long long* o8 = (unsigned long long*)(hb + (size_t)m * DM) + lane;
; #pragma unroll
;             for (int j = 0; j < 4; ++j) { const f32x4 gg = ((const f32x4*)g)[lane + 64 * j], bb = ((const f32x4*)bta)[lane + 64 * j];
;                 const f32x4 o = v[q][j] * rstd * gg + bb; if (write_h) xr[64 * j] = o;
;                 o8[64 * j] = (unsigned long long)pk2(o.x, o.y) | ((unsigned long long)pk2(o.z, o.w) << 32); }
.LBB0_3036:
	s_or_b64 exec, exec, s[0:1]
	s_add_u32 s20, s50, 0x600000
	s_addc_u32 s21, s51, 0
	s_add_i32 s0, 0, 0x279f8
	s_waitcnt lgkmcnt(0)
	v_mov_b32_e32 v0, s0
	s_barrier
	ds_read2_b64 v[0:3], v0 offset1:1
	v_readlane_b32 s0, v254, 15
	s_ashr_i32 s9, s0, 6
	v_readlane_b32 s0, v254, 6
	s_add_i32 s8, s9, s0
	s_waitcnt vmcnt(9)
	v_and_b32_e32 v160, 63, v206
	s_cmp_lt_i32 s8, 0x8000
	s_waitcnt lgkmcnt(0)
	v_readfirstlane_b32 s6, v0
	v_readfirstlane_b32 s7, v1
	v_readfirstlane_b32 s22, v2
	v_readfirstlane_b32 s23, v3
	v_mov_b32_e32 v0, v160
	s_cselect_b64 s[10:11], -1, 0
	s_cmpk_gt_i32 s8, 0x7fff
	s_cbranch_scc1 .LBB0_3043
	v_ashrrev_i32_e32 v1, 31, v0
	v_lshlrev_b64 v[2:3], 4, v[0:1]
	v_lshlrev_b32_e32 v4, 2, v0
	s_lshl_b32 s4, s2, 4
	s_lshl_b32 s5, s9, 1
	v_lshl_add_u64 v[32:33], s[48:49], 0, v[2:3]
	v_xor_b32_e32 v42, 64, v4
	v_xor_b32_e32 v43, 0x80, v4
	v_cmp_eq_u32_e64 s[0:1], 0, v0
	v_lshl_add_u64 v[34:35], v[0:1], 3, s[94:95]
	v_lshl_add_u64 v[36:37], s[6:7], 0, v[2:3]
	v_lshl_add_u64 v[38:39], s[22:23], 0, v[2:3]
	flat_load_dwordx4 v[64:67], v[36:37]
	flat_load_dwordx4 v[68:71], v[36:37] offset:1024
	flat_load_dwordx4 v[72:75], v[36:37] offset:2048
	flat_load_dwordx4 v[76:79], v[36:37] offset:3072
	flat_load_dwordx4 v[80:83], v[38:39]
	flat_load_dwordx4 v[84:87], v[38:39] offset:1024
	flat_load_dwordx4 v[88:91], v[38:39] offset:2048
	flat_load_dwordx4 v[92:95], v[38:39] offset:3072
	s_waitcnt vmcnt(0) lgkmcnt(0)
	s_add_i32 s22, s4, s5
	s_lshl_b32 s4, s58, 5
	s_lshl_b32 s5, s58, 4
	v_mov_b32_e32 v44, 0x3727c5ac
	s_mov_b32 s14, 0xf800000
	v_mov_b32_e32 v45, 0x260
	v_mov_b32_e32 v46, 0
	s_mov_b32 s26, s8
	s_branch .LBB0_3039
.LBB0_3038:
	s_or_b64 exec, exec, s[6:7]
	v_pk_mul_f32 v[14:15], v[18:19], v[12:13] op_sel_hi:[1,0]
	v_pk_mul_f32 v[16:17], v[16:17], v[12:13] op_sel_hi:[1,0]
	s_lshl_b64 s[6:7], s[24:25], 11
	v_lshl_add_u64 v[28:29], v[34:35], 0, s[6:7]
	v_pk_mul_f32 v[10:11], v[10:11], v[12:13] op_sel_hi:[1,0]
	v_pk_mul_f32 v[8:9], v[8:9], v[12:13] op_sel_hi:[1,0]
	v_pk_mul_f32 v[6:7], v[6:7], v[12:13] op_sel_hi:[1,0]
	v_pk_mul_f32 v[4:5], v[4:5], v[12:13] op_sel_hi:[1,0]
	v_pk_mul_f32 v[2:3], v[2:3], v[12:13] op_sel_hi:[1,0]
	v_pk_mul_f32 v[0:1], v[0:1], v[12:13] op_sel_hi:[1,0]
	s_add_i32 s26, s24, s54
	s_add_i32 s22, s22, s4
	s_cmp_lt_i32 s26, 0x8000
	v_pk_fma_f32 v[14:15], v[14:15], v[66:67], v[82:83]
	v_pk_fma_f32 v[16:17], v[16:17], v[64:65], v[80:81]
	s_nop 0
	v_cvt_pk_bf16_f32 v16, v16, v17
	v_cvt_pk_bf16_f32 v17, v14, v15
	global_store_dwordx2 v[28:29], v[16:17], off
	v_pk_fma_f32 v[10:11], v[10:11], v[70:71], v[86:87]
	v_pk_fma_f32 v[8:9], v[8:9], v[68:69], v[84:85]
	s_nop 0
	v_cvt_pk_bf16_f32 v8, v8, v9
	v_cvt_pk_bf16_f32 v9, v10, v11
	global_store_dwordx2 v[28:29], v[8:9], off offset:512
	v_pk_fma_f32 v[6:7], v[6:7], v[74:75], v[90:91]
	v_pk_fma_f32 v[4:5], v[4:5], v[72:73], v[88:89]
	s_nop 0
	v_cvt_pk_bf16_f32 v4, v4, v5
	v_cvt_pk_bf16_f32 v5, v6, v7
	global_store_dwordx2 v[28:29], v[4:5], off offset:1024
	v_pk_fma_f32 v[2:3], v[2:3], v[78:79], v[94:95]
	v_pk_fma_f32 v[0:1], v[0:1], v[76:77], v[92:93]
	s_nop 0
	v_cvt_pk_bf16_f32 v0, v0, v1
	v_cvt_pk_bf16_f32 v1, v2, v3
	global_store_dwordx2 v[28:29], v[0:1], off offset:1536
	s_cbranch_scc0 .LBB0_3043

; DEV unsigned pk2(float lo, float hi) { f32x2_ v; v.x = lo; v.y = hi; return __builtin_bit_cast(unsigned, __builtin_convertvector(v, bf16x2_)); }
; DEV void ln_rows(float* hbuf, bf16* hb, const float* g, const float* bta, float* stats, bool write_h, int gw, int NGW, int lane) {
;     ...
;         for (int q = 0; q < 2; ++q) {
;             const int m = m0 + q * NGW;
;             const float mean = wave_sum(s[q], lane) * (1.f / DM); float s2 = 0.f;
; #pragma unroll
;             for (int j = 0; j < 4; ++j) { v[q][j] = v[q][j] - mean; s2 += (v[q][j].x * v[q][j].x + v[q][j].y * v[q][j].y) + (v[q][j].z * v[q][j].z + v[q][j].w * v[q][j].w); }
;             const float rstd = 1.f / sqrtf(wave_sum(s2, lane) * (1.f / DM) + 1e-5f);
;             if (lane == 0) { f32x2_ st2; st2.x = mean; st2.y = rstd; *(f32x2_*)(stats + 2 * m) = st2; }
;             f32x4* xr = (f32x4*)(hbuf + (size_t)m * DM) + lane;
;             unsigned long long* o8 = (unsigned long long*)(hb + (size_t)m * DM) + lane;
; #pragma unroll
;             for (int j = 0; j < 4; ++j) { const f32x4 gg = ((const f32x4*)g)[lane + 64 * j], bb = ((const f32x4*)bta)[lane + 64 * j];
;                 const f32x4 o = v[q][j] * rstd * gg + bb; if (write_h) xr[64 * j] = o;
;                 o8[64 * j] = (unsigned long long)pk2(o.x, o.y) | ((unsigned long long)pk2(o.z, o.w) << 32); }
.LBB0_3041:
	s_or_b64 exec, exec, s[6:7]
	v_pk_mul_f32 v[40:41], v[40:41], v[22:23] op_sel_hi:[1,0]
	v_pk_mul_f32 v[28:29], v[28:29], v[22:23] op_sel_hi:[1,0]
	s_lshl_b64 s[6:7], s[26:27], 11
	v_lshl_add_u64 v[56:57], v[34:35], 0, s[6:7]
	v_pk_mul_f32 v[24:25], v[24:25], v[22:23] op_sel_hi:[1,0]
	s_waitcnt vmcnt(1)
	v_add_f32_e32 v47, v6, v7
	s_waitcnt lgkmcnt(0)
	v_pk_fma_f32 v[40:41], v[40:41], v[66:67], v[82:83]
	v_pk_fma_f32 v[28:29], v[28:29], v[64:65], v[80:81]
	s_nop 0
	v_cvt_pk_bf16_f32 v28, v28, v29
	v_cvt_pk_bf16_f32 v29, v40, v41
	global_store_dwordx2 v[56:57], v[28:29], off
	v_pk_mul_f32 v[28:29], v[30:31], v[22:23] op_sel_hi:[1,0]
	v_add_f32_e32 v23, v16, v17
	v_add_f32_e32 v40, v10, v11
	v_add_f32_e32 v41, v4, v5
	v_pk_fma_f32 v[28:29], v[28:29], v[70:71], v[86:87]
	v_pk_fma_f32 v[24:25], v[24:25], v[68:69], v[84:85]
	v_add_f32_e32 v52, v0, v1
	v_cvt_pk_bf16_f32 v24, v24, v25
	v_cvt_pk_bf16_f32 v25, v28, v29
	global_store_dwordx2 v[56:57], v[24:25], off offset:512
	v_add_f32_e32 v24, v18, v19
	v_add_f32_e32 v25, v8, v9
	v_add_f32_e32 v23, v23, v24
	v_add_f32_e32 v24, v25, v40
	v_add_f32_e32 v23, 0, v23
	v_add_f32_e32 v53, v2, v3
	v_add_f32_e32 v25, v41, v47
	v_add_f32_e32 v23, v23, v24
	v_add_f32_e32 v40, v52, v53
	v_add_f32_e32 v23, v23, v25
	v_add_f32_e32 v23, v23, v40
	s_nop 1
	v_add_f32_dpp v23, v23, v23 quad_perm:[1,0,3,2] row_mask:0xf bank_mask:0xf bound_ctrl:1
	s_nop 1
	v_add_f32_dpp v23, v23, v23 quad_perm:[2,3,0,1] row_mask:0xf bank_mask:0xf bound_ctrl:1
	s_nop 1
	v_add_f32_dpp v23, v23, v23 row_half_mirror row_mask:0xf bank_mask:0xf bound_ctrl:1
	s_nop 1
	v_add_f32_dpp v23, v23, v23 row_mirror row_mask:0xf bank_mask:0xf bound_ctrl:1
	ds_bpermute_b32 v24, v42, v23
	s_waitcnt lgkmcnt(0)
	v_add_f32_e32 v23, v23, v24
	v_pk_mul_f32 v[24:25], v[26:27], v[22:23] op_sel_hi:[1,0]
	v_pk_mul_f32 v[26:27], v[20:21], v[22:23] op_sel_hi:[1,0]
	ds_bpermute_b32 v40, v43, v23
	s_waitcnt lgkmcnt(0)
	v_add_f32_e32 v20, v23, v40
	v_fmamk_f32 v19, v20, 0xba800000, v19
	v_fmamk_f32 v17, v20, 0xba800000, v17
	v_fmamk_f32 v11, v20, 0xba800000, v11
	v_fmamk_f32 v9, v20, 0xba800000, v9
	v_fmamk_f32 v18, v20, 0xba800000, v18
	v_fmac_f32_e32 v16, 0xba800000, v20
	v_fmamk_f32 v10, v20, 0xba800000, v10
	v_fmac_f32_e32 v8, 0xba800000, v20
	v_fmamk_f32 v7, v20, 0xba800000, v7
	v_fmamk_f32 v5, v20, 0xba800000, v5
	v_mul_f32_e32 v21, v17, v17
	v_mul_f32_e32 v23, v19, v19
	v_mul_f32_e32 v40, v9, v9
	v_mul_f32_e32 v41, v11, v11
	v_fmamk_f32 v6, v20, 0xba800000, v6
	v_fmac_f32_e32 v4, 0xba800000, v20
	v_fmamk_f32 v3, v20, 0xba800000, v3
	v_fmamk_f32 v1, v20, 0xba800000, v1
	v_mul_f32_e32 v47, v5, v5
	v_fmac_f32_e32 v21, v16, v16
	v_fmac_f32_e32 v23, v18, v18
	v_fmac_f32_e32 v40, v8, v8
	v_fmac_f32_e32 v41, v10, v10
	v_fmamk_f32 v2, v20, 0xba800000, v2
	v_fmac_f32_e32 v0, 0xba800000, v20
	v_fmac_f32_e32 v47, v4, v4
	v_add_f32_e32 v21, v21, v23
	v_add_f32_e32 v23, v40, v41
	v_add_f32_e32 v21, v21, v23
	v_pk_fma_f32 v[24:25], v[24:25], v[74:75], v[90:91]
	v_pk_fma_f32 v[26:27], v[26:27], v[72:73], v[88:89]
	v_mul_f32_e32 v48, v7, v7
	v_cvt_pk_bf16_f32 v26, v26, v27
	v_cvt_pk_bf16_f32 v27, v24, v25
	global_store_dwordx2 v[56:57], v[26:27], off offset:1024
	v_mul_f32_e32 v49, v1, v1
	v_mul_f32_e32 v50, v3, v3
	v_fmac_f32_e32 v48, v6, v6
	v_fmac_f32_e32 v49, v0, v0
	v_fmac_f32_e32 v50, v2, v2
	v_add_f32_e32 v40, v47, v48
	v_add_f32_e32 v41, v49, v50
	v_add_f32_e32 v21, v40, v21
	v_add_f32_e32 v21, v41, v21
	s_nop 1
	v_add_f32_dpp v21, v21, v21 quad_perm:[1,0,3,2] row_mask:0xf bank_mask:0xf bound_ctrl:1
	s_nop 1
	v_add_f32_dpp v21, v21, v21 quad_perm:[2,3,0,1] row_mask:0xf bank_mask:0xf bound_ctrl:1
	s_nop 1
	v_add_f32_dpp v21, v21, v21 row_half_mirror row_mask:0xf bank_mask:0xf bound_ctrl:1
	s_nop 1
	v_add_f32_dpp v21, v21, v21 row_mirror row_mask:0xf bank_mask:0xf bound_ctrl:1
	ds_bpermute_b32 v23, v42, v21
	s_waitcnt lgkmcnt(0)
	v_add_f32_e32 v21, v21, v23
	ds_bpermute_b32 v23, v43, v21
	s_waitcnt lgkmcnt(0)
	v_add_f32_e32 v21, v21, v23
	v_fmamk_f32 v21, v21, 0x3a800000, v44
	v_mul_f32_e32 v23, 0x4f800000, v21
	v_cmp_gt_f32_e32 vcc, s14, v21
	s_nop 1
	v_cndmask_b32_e32 v21, v21, v23, vcc
	v_sqrt_f32_e32 v23, v21
	s_nop 0
	v_add_u32_e32 v40, -1, v23
	v_add_u32_e32 v41, 1, v23
	v_fma_f32 v47, -v40, v23, v21
	v_fma_f32 v48, -v41, v23, v21
	v_cmp_ge_f32_e64 s[6:7], 0, v47
	v_pk_mul_f32 v[14:15], v[14:15], v[22:23] op_sel_hi:[1,0]
	s_nop 0
	v_cndmask_b32_e64 v23, v23, v40, s[6:7]
	v_cmp_lt_f32_e64 s[6:7], 0, v48
	v_pk_fma_f32 v[14:15], v[14:15], v[78:79], v[94:95]
	v_cndmask_b32_e64 v23, v23, v41, s[6:7]
	v_mul_f32_e32 v40, 0x37800000, v23
	v_cndmask_b32_e32 v23, v23, v40, vcc
	v_cmp_class_f32_e32 vcc, v21, v45
	s_nop 1
	v_cndmask_b32_e32 v21, v23, v21, vcc
	v_div_scale_f32 v23, s[6:7], v21, v21, 1.0
	v_rcp_f32_e32 v40, v23
	v_pk_mul_f32 v[12:13], v[12:13], v[22:23] op_sel_hi:[1,0]
	v_div_scale_f32 v22, vcc, 1.0, v21, 1.0
	v_fma_f32 v41, -v23, v40, 1.0
	v_fmac_f32_e32 v40, v41, v40
	v_mul_f32_e32 v41, v22, v40
	v_fma_f32 v47, -v23, v41, v22
	v_fmac_f32_e32 v41, v47, v40
	v_fma_f32 v22, -v23, v41, v22
	v_pk_fma_f32 v[12:13], v[12:13], v[76:77], v[92:93]
	v_div_fmas_f32 v22, v22, v40, v41
	v_cvt_pk_bf16_f32 v12, v12, v13
	v_cvt_pk_bf16_f32 v13, v14, v15
	global_store_dwordx2 v[56:57], v[12:13], off offset:1536
	v_div_fixup_f32 v12, v22, v21, 1.0
	s_and_saveexec_b64 s[6:7], s[0:1]
	s_cbranch_execz .LBB0_3038
	s_add_i32 s12, s5, s22
	s_ashr_i32 s13, s12, 31
	s_lshl_b64 s[12:13], s[12:13], 2
	s_add_u32 s12, s20, s12
	v_mul_f32_e32 v14, 0x3a800000, v20
	s_addc_u32 s13, s21, s13
	v_mov_b32_e32 v15, v12
	global_store_dwordx2 v46, v[14:15], s[12:13]
	s_branch .LBB0_3038

; DEV unsigned pk2(float lo, float hi) { f32x2_ v; v.x = lo; v.y = hi; return __builtin_bit_cast(unsigned, __builtin_convertvector(v, bf16x2_)); }
; DEV void ln_rows(float* hbuf, bf16* hb, const float* g, const float* bta, float* stats, bool write_h, int gw, int NGW, int lane) {
;     ...
;             if (lane == 0) { f32x2_ st2; st2.x = mean; st2.y = rstd; *(f32x2_*)(stats + 2 * m) = st2; }
;             f32x4* xr = (f32x4*)(hbuf + (size_t)m * DM) + lane;
;             unsigned long long* o8 = (unsigned long long*)(hb + (size_t)m * DM) + lane;
; #pragma unroll
;             for (int j = 0; j < 4; ++j) { const f32x4 gg = ((const f32x4*)g)[lane + 64 * j], bb = ((const f32x4*)bta)[lane + 64 * j];
;                 const f32x4 o = v[q][j] * rstd * gg + bb; if (write_h) xr[64 * j] = o;
;                 o8[64 * j] = (unsigned long long)pk2(o.x, o.y) | ((unsigned long long)pk2(o.z, o.w) << 32); }
.LBB0_3264:
	s_or_b64 exec, exec, s[0:1]
	s_add_i32 s0, 0, 0x27a18
	s_waitcnt lgkmcnt(0)
	v_mov_b32_e32 v0, s0
	s_barrier
	ds_read2_b64 v[0:3], v0 offset1:1
	s_andn2_b64 vcc, exec, s[10:11]
	s_waitcnt lgkmcnt(0)
	v_readfirstlane_b32 s4, v0
	v_readfirstlane_b32 s5, v1
	v_readfirstlane_b32 s6, v2
	v_readfirstlane_b32 s7, v3
	s_cbranch_vccnz .LBB0_3271
	v_ashrrev_i32_e32 v161, 31, v160
	v_lshlrev_b64 v[0:1], 4, v[160:161]
	v_lshlrev_b32_e32 v2, 2, v160
	s_lshl_b32 s2, s2, 4
	s_lshl_b32 s3, s9, 1
	v_lshl_add_u64 v[32:33], s[48:49], 0, v[0:1]
	v_xor_b32_e32 v46, 64, v2
	v_xor_b32_e32 v47, 0x80, v2
	v_cmp_eq_u32_e64 s[0:1], 0, v160
	v_lshl_add_u64 v[34:35], v[160:161], 3, s[94:95]
	v_lshl_add_u64 v[36:37], s[4:5], 0, v[0:1]
	v_lshl_add_u64 v[38:39], s[6:7], 0, v[0:1]
	flat_load_dwordx4 v[64:67], v[36:37]
	flat_load_dwordx4 v[68:71], v[36:37] offset:1024
	flat_load_dwordx4 v[72:75], v[36:37] offset:2048
	flat_load_dwordx4 v[76:79], v[36:37] offset:3072
	flat_load_dwordx4 v[80:83], v[38:39]
	flat_load_dwordx4 v[84:87], v[38:39] offset:1024
	flat_load_dwordx4 v[88:91], v[38:39] offset:2048
	flat_load_dwordx4 v[92:95], v[38:39] offset:3072
	s_waitcnt vmcnt(0) lgkmcnt(0)
	s_add_i32 s4, s2, s3
	s_lshl_b32 s10, s58, 5
	s_lshl_b32 s11, s58, 4
	v_mov_b32_e32 v48, 0x3727c5ac
	s_mov_b32 s12, 0xf800000
	v_mov_b32_e32 v49, 0x260
	v_mov_b32_e32 v50, 0
	s_branch .LBB0_3267
.LBB0_3266:
	s_or_b64 exec, exec, s[2:3]
	v_pk_mul_f32 v[14:15], v[18:19], v[12:13] op_sel_hi:[1,0]
	v_pk_mul_f32 v[18:19], v[16:17], v[12:13] op_sel_hi:[1,0]
	s_lshl_b64 s[2:3], s[6:7], 11
	v_lshl_add_u64 v[28:29], v[34:35], 0, s[2:3]
	v_pk_mul_f32 v[10:11], v[10:11], v[12:13] op_sel_hi:[1,0]
	v_pk_mul_f32 v[8:9], v[8:9], v[12:13] op_sel_hi:[1,0]
	v_pk_mul_f32 v[6:7], v[6:7], v[12:13] op_sel_hi:[1,0]
	v_pk_mul_f32 v[4:5], v[4:5], v[12:13] op_sel_hi:[1,0]
	v_pk_mul_f32 v[2:3], v[2:3], v[12:13] op_sel_hi:[1,0]
	v_pk_mul_f32 v[0:1], v[0:1], v[12:13] op_sel_hi:[1,0]
	s_add_i32 s8, s6, s54
	s_add_i32 s4, s4, s10
	s_cmp_lt_i32 s8, 0x8000
	v_pk_fma_f32 v[16:17], v[14:15], v[66:67], v[82:83]
	v_pk_fma_f32 v[14:15], v[18:19], v[64:65], v[80:81]
	global_store_dwordx4 v[40:41], v[14:17], off
	s_nop 1
	v_cvt_pk_bf16_f32 v14, v14, v15
	v_cvt_pk_bf16_f32 v15, v16, v17
	global_store_dwordx2 v[28:29], v[14:15], off
	v_pk_fma_f32 v[10:11], v[10:11], v[70:71], v[86:87]
	v_pk_fma_f32 v[8:9], v[8:9], v[68:69], v[84:85]
	global_store_dwordx4 v[40:41], v[8:11], off offset:1024
	s_nop 1
	v_cvt_pk_bf16_f32 v8, v8, v9
	v_cvt_pk_bf16_f32 v9, v10, v11
	global_store_dwordx2 v[28:29], v[8:9], off offset:512
	v_pk_fma_f32 v[6:7], v[6:7], v[74:75], v[90:91]
	v_pk_fma_f32 v[4:5], v[4:5], v[72:73], v[88:89]
	global_store_dwordx4 v[40:41], v[4:7], off offset:2048
	s_nop 1
	v_cvt_pk_bf16_f32 v4, v4, v5
	v_cvt_pk_bf16_f32 v5, v6, v7
	global_store_dwordx2 v[28:29], v[4:5], off offset:1024
	v_pk_fma_f32 v[2:3], v[2:3], v[78:79], v[94:95]
	v_pk_fma_f32 v[0:1], v[0:1], v[76:77], v[92:93]
	global_store_dwordx4 v[40:41], v[0:3], off offset:3072
	s_nop 1
	v_cvt_pk_bf16_f32 v0, v0, v1
	v_cvt_pk_bf16_f32 v1, v2, v3
	global_store_dwordx2 v[28:29], v[0:1], off offset:1536
	s_cbranch_scc0 .LBB0_3271

; DEV unsigned pk2(float lo, float hi) { f32x2_ v; v.x = lo; v.y = hi; return __builtin_bit_cast(unsigned, __builtin_convertvector(v, bf16x2_)); }
; DEV void ln_rows(float* hbuf, bf16* hb, const float* g, const float* bta, float* stats, bool write_h, int gw, int NGW, int lane) {
;     ...
;         for (int q = 0; q < 2; ++q) {
;             const int m = m0 + q * NGW;
;             const float mean = wave_sum(s[q], lane) * (1.f / DM); float s2 = 0.f;
; #pragma unroll
;             for (int j = 0; j < 4; ++j) { v[q][j] = v[q][j] - mean; s2 += (v[q][j].x * v[q][j].x + v[q][j].y * v[q][j].y) + (v[q][j].z * v[q][j].z + v[q][j].w * v[q][j].w); }
;             const float rstd = 1.f / sqrtf(wave_sum(s2, lane) * (1.f / DM) + 1e-5f);
;             if (lane == 0) { f32x2_ st2; st2.x = mean; st2.y = rstd; *(f32x2_*)(stats + 2 * m) = st2; }
;             f32x4* xr = (f32x4*)(hbuf + (size_t)m * DM) + lane;
;             unsigned long long* o8 = (unsigned long long*)(hb + (size_t)m * DM) + lane;
; #pragma unroll
;             for (int j = 0; j < 4; ++j) { const f32x4 gg = ((const f32x4*)g)[lane + 64 * j], bb = ((const f32x4*)bta)[lane + 64 * j];
;                 const f32x4 o = v[q][j] * rstd * gg + bb; if (write_h) xr[64 * j] = o;
;                 o8[64 * j] = (unsigned long long)pk2(o.x, o.y) | ((unsigned long long)pk2(o.z, o.w) << 32); }
.LBB0_3269:
	s_or_b64 exec, exec, s[2:3]
	v_pk_mul_f32 v[44:45], v[44:45], v[22:23] op_sel_hi:[1,0]
	v_pk_mul_f32 v[28:29], v[28:29], v[22:23] op_sel_hi:[1,0]
	s_lshl_b64 s[2:3], s[8:9], 11
	v_lshl_add_u64 v[60:61], v[34:35], 0, s[2:3]
	v_pk_mul_f32 v[24:25], v[24:25], v[22:23] op_sel_hi:[1,0]
	s_waitcnt vmcnt(1)
	v_add_f32_e32 v51, v6, v7
	s_waitcnt lgkmcnt(0)
	v_pk_fma_f32 v[54:55], v[44:45], v[66:67], v[82:83]
	v_pk_fma_f32 v[52:53], v[28:29], v[64:65], v[80:81]
	v_cvt_pk_bf16_f32 v29, v54, v55
	v_cvt_pk_bf16_f32 v28, v52, v53
	global_store_dwordx4 v[42:43], v[52:55], off
	global_store_dwordx2 v[60:61], v[28:29], off
	v_pk_mul_f32 v[28:29], v[30:31], v[22:23] op_sel_hi:[1,0]
	v_add_f32_e32 v23, v16, v17
	v_add_f32_e32 v44, v10, v11
	v_add_f32_e32 v45, v4, v5
	v_pk_fma_f32 v[30:31], v[28:29], v[70:71], v[86:87]
	v_pk_fma_f32 v[28:29], v[24:25], v[68:69], v[84:85]
	v_cvt_pk_bf16_f32 v25, v30, v31
	v_cvt_pk_bf16_f32 v24, v28, v29
	global_store_dwordx4 v[42:43], v[28:31], off offset:1024
	global_store_dwordx2 v[60:61], v[24:25], off offset:512
	v_add_f32_e32 v24, v18, v19
	v_add_f32_e32 v25, v8, v9
	v_add_f32_e32 v23, v23, v24
	v_add_f32_e32 v24, v25, v44
	v_add_f32_e32 v23, 0, v23
	v_add_f32_e32 v56, v0, v1
	v_add_f32_e32 v57, v2, v3
	v_add_f32_e32 v25, v45, v51
	v_add_f32_e32 v23, v23, v24
	v_add_f32_e32 v44, v56, v57
	v_add_f32_e32 v23, v23, v25
	v_add_f32_e32 v23, v23, v44
	s_nop 1
	v_add_f32_dpp v23, v23, v23 quad_perm:[1,0,3,2] row_mask:0xf bank_mask:0xf bound_ctrl:1
	s_nop 1
	v_add_f32_dpp v23, v23, v23 quad_perm:[2,3,0,1] row_mask:0xf bank_mask:0xf bound_ctrl:1
	s_nop 1
	v_add_f32_dpp v23, v23, v23 row_half_mirror row_mask:0xf bank_mask:0xf bound_ctrl:1
	s_nop 1
	v_add_f32_dpp v23, v23, v23 row_mirror row_mask:0xf bank_mask:0xf bound_ctrl:1
	ds_bpermute_b32 v24, v46, v23
	s_waitcnt lgkmcnt(0)
	v_add_f32_e32 v23, v23, v24
	v_pk_mul_f32 v[24:25], v[26:27], v[22:23] op_sel_hi:[1,0]
	v_pk_mul_f32 v[44:45], v[20:21], v[22:23] op_sel_hi:[1,0]
	ds_bpermute_b32 v51, v47, v23
	s_waitcnt lgkmcnt(0)
	v_add_f32_e32 v20, v23, v51
	v_fmamk_f32 v19, v20, 0xba800000, v19
	v_fmamk_f32 v17, v20, 0xba800000, v17
	v_fmamk_f32 v11, v20, 0xba800000, v11
	v_fmamk_f32 v9, v20, 0xba800000, v9
	v_fmamk_f32 v18, v20, 0xba800000, v18
	v_fmac_f32_e32 v16, 0xba800000, v20
	v_fmamk_f32 v10, v20, 0xba800000, v10
	v_fmac_f32_e32 v8, 0xba800000, v20
	v_fmamk_f32 v7, v20, 0xba800000, v7
	v_fmamk_f32 v5, v20, 0xba800000, v5
	v_mul_f32_e32 v21, v17, v17
	v_mul_f32_e32 v23, v19, v19
	v_fmamk_f32 v6, v20, 0xba800000, v6
	v_fmac_f32_e32 v4, 0xba800000, v20
	v_fmamk_f32 v3, v20, 0xba800000, v3
	v_fmamk_f32 v1, v20, 0xba800000, v1
	v_mul_f32_e32 v51, v5, v5
	v_fmac_f32_e32 v21, v16, v16
	v_fmac_f32_e32 v23, v18, v18
	v_fmamk_f32 v2, v20, 0xba800000, v2
	v_fmac_f32_e32 v0, 0xba800000, v20
	v_fmac_f32_e32 v51, v4, v4
	v_add_f32_e32 v21, v21, v23
	v_pk_fma_f32 v[26:27], v[24:25], v[74:75], v[90:91]
	v_pk_fma_f32 v[24:25], v[44:45], v[72:73], v[88:89]
	global_store_dwordx4 v[42:43], v[24:27], off offset:2048
	v_mul_f32_e32 v44, v9, v9
	v_mul_f32_e32 v45, v11, v11
	v_cvt_pk_bf16_f32 v24, v24, v25
	v_cvt_pk_bf16_f32 v25, v26, v27
	global_store_dwordx2 v[60:61], v[24:25], off offset:1024
	v_mul_f32_e32 v52, v7, v7
	v_fmac_f32_e32 v44, v8, v8
	v_fmac_f32_e32 v45, v10, v10
	v_mul_f32_e32 v53, v1, v1
	v_mul_f32_e32 v54, v3, v3
	v_fmac_f32_e32 v52, v6, v6
	v_add_f32_e32 v23, v44, v45
	v_fmac_f32_e32 v53, v0, v0
	v_fmac_f32_e32 v54, v2, v2
	v_add_f32_e32 v44, v51, v52
	v_add_f32_e32 v21, v21, v23
	v_add_f32_e32 v45, v53, v54
	v_add_f32_e32 v21, v44, v21
	v_add_f32_e32 v21, v45, v21
	s_nop 1
	v_add_f32_dpp v21, v21, v21 quad_perm:[1,0,3,2] row_mask:0xf bank_mask:0xf bound_ctrl:1
	s_nop 1
	v_add_f32_dpp v21, v21, v21 quad_perm:[2,3,0,1] row_mask:0xf bank_mask:0xf bound_ctrl:1
	s_nop 1
	v_add_f32_dpp v21, v21, v21 row_half_mirror row_mask:0xf bank_mask:0xf bound_ctrl:1
	s_nop 1
	v_add_f32_dpp v21, v21, v21 row_mirror row_mask:0xf bank_mask:0xf bound_ctrl:1
	ds_bpermute_b32 v23, v46, v21
	s_waitcnt lgkmcnt(0)
	v_add_f32_e32 v21, v21, v23
	ds_bpermute_b32 v23, v47, v21
	s_waitcnt lgkmcnt(0)
	v_add_f32_e32 v21, v21, v23
	v_fmamk_f32 v21, v21, 0x3a800000, v48
	v_mul_f32_e32 v23, 0x4f800000, v21
	v_cmp_gt_f32_e32 vcc, s12, v21
	s_nop 1
	v_cndmask_b32_e32 v21, v21, v23, vcc
	v_sqrt_f32_e32 v23, v21
	s_nop 0
	v_add_u32_e32 v44, -1, v23
	v_add_u32_e32 v45, 1, v23
	v_fma_f32 v51, -v44, v23, v21
	v_fma_f32 v52, -v45, v23, v21
	v_cmp_ge_f32_e64 s[2:3], 0, v51
	v_pk_mul_f32 v[14:15], v[14:15], v[22:23] op_sel_hi:[1,0]
	s_nop 0
	v_cndmask_b32_e64 v23, v23, v44, s[2:3]
	v_cmp_lt_f32_e64 s[2:3], 0, v52
	v_pk_fma_f32 v[14:15], v[14:15], v[78:79], v[94:95]
	v_cndmask_b32_e64 v23, v23, v45, s[2:3]
	v_mul_f32_e32 v44, 0x37800000, v23
	v_cndmask_b32_e32 v23, v23, v44, vcc
	v_cmp_class_f32_e32 vcc, v21, v49
	s_nop 1
	v_cndmask_b32_e32 v21, v23, v21, vcc
	v_div_scale_f32 v23, s[2:3], v21, v21, 1.0
	v_rcp_f32_e32 v44, v23
	v_pk_mul_f32 v[12:13], v[12:13], v[22:23] op_sel_hi:[1,0]
	v_div_scale_f32 v22, vcc, 1.0, v21, 1.0
	v_fma_f32 v45, -v23, v44, 1.0
	v_fmac_f32_e32 v44, v45, v44
	v_mul_f32_e32 v45, v22, v44
	v_fma_f32 v51, -v23, v45, v22
	v_fmac_f32_e32 v45, v51, v44
	v_fma_f32 v22, -v23, v45, v22
	v_pk_fma_f32 v[12:13], v[12:13], v[76:77], v[92:93]
	v_div_fmas_f32 v22, v22, v44, v45
	global_store_dwordx4 v[42:43], v[12:15], off offset:3072
	s_nop 1
	v_cvt_pk_bf16_f32 v12, v12, v13
	v_cvt_pk_bf16_f32 v13, v14, v15
	global_store_dwordx2 v[60:61], v[12:13], off offset:1536
	v_div_fixup_f32 v12, v22, v21, 1.0
	s_and_saveexec_b64 s[2:3], s[0:1]
	s_cbranch_execz .LBB0_3266
	s_add_i32 s8, s11, s4
	s_ashr_i32 s9, s8, 31
	s_lshl_b64 s[8:9], s[8:9], 2
	s_add_u32 s8, s18, s8
	v_mul_f32_e32 v14, 0x3a800000, v20
	s_addc_u32 s9, s19, s9
	v_mov_b32_e32 v15, v12
	global_store_dwordx2 v50, v[14:15], s[8:9]
	s_branch .LBB0_3266
